# scan compute loop hand-scheduled (2-step LDS prefetch, skewed B(t)||A(t+1)), loader vmcnt waits re-derived, attention S/PV LDS fragment reads pipelined through a 4-deep register ring
# speedup vs baseline: 1.0970x; 1.0970x over previous
; #define LAS __attribute__((address_space(3)))
; __device__ __forceinline__ void attn_phase(LAS unsigned char* lds, const h16* Qb, const h16* Kb, const h16* Vt, h16* AO, const float* rel_bias, const float* lam, const float* subg, float lambda_init) {
;     ...
;                     if (64 * kt + 32 * kb <= q0 + 32 * rg + 31) {
;                         f32x16 S0;
; #pragma unroll
;                         for (int r = 0; r < 16; ++r) S0[r] = 0.f;
;                         LAS unsigned char* ks = cb + (32 * kb + l32) * 512 + mp * 256;
; #pragma unroll
;                         for (int k = 0; k < 8; ++k) {
;                             const h16x8 a0 = *(LAS h16x8*)(ks + (((2 * k + hh) ^ xk) << 4));
;                             S0 = __builtin_amdgcn_mfma_f32_32x32x16_f16(a0, Qf[k], S0, 0, 0, 0);
;                         }
;                         if (near) {
; #pragma unroll
;                             for (int r = 0; r < 16; ++r) {
;                                 const int kp = 64 * kt + 32 * kb + (r >> 2) * 8 + hh * 4 + (r & 3); const int d0 = qrow - kp;
;                                 const int di = d0 < 0 ? 0 : (d0 > 128 ? 128 : d0); const float bv = lut[di];
;                                 S0[r] = d0 < 0 ? -1e30f : S0[r] + bv;
.LBB0_168:
	s_add_i32 s22, s21, 0
	s_cmp_ge_i32 s20, s35
	s_cselect_b64 s[20:21], -1, 0
	s_add_i32 s23, s22, s81
	v_add_u32_e32 v0, s23, v226
	v_cndmask_b32_e64 v2, 0, 1, s[20:21]
	v_add_u32_e32 v10, s22, v225
	s_cmp_gt_i32 s50, s48
	v_add_u32_e32 v213, v0, v227
	v_add_u32_e32 v212, v0, v228
	v_add_u32_e32 v245, v0, v229
	v_add_u32_e32 v15, v0, v230
	v_add_u32_e32 v14, v0, v231
	v_add_u32_e32 v13, v0, v232
	v_add_u32_e32 v12, v0, v233
	v_add_u32_e32 v11, v0, v234
	v_cmp_ne_u32_e64 s[38:39], 1, v2
	s_cbranch_scc1 .LBB0_206
	ds_read_b128 v[160:163], v213
	ds_read_b128 v[164:167], v212
	ds_read_b128 v[168:171], v245
	ds_read_b128 v[172:175], v15
	s_and_b64 vcc, exec, s[38:39]
	s_waitcnt lgkmcnt(3)
	v_mfma_f32_32x32x16_f16 v[144:159], v[160:163], v[176:179], 0
	ds_read_b128 v[160:163], v14
	s_waitcnt lgkmcnt(3)
	v_mfma_f32_32x32x16_f16 v[144:159], v[164:167], v[180:183], v[144:159]
	ds_read_b128 v[164:167], v13
	s_waitcnt lgkmcnt(3)
	v_mfma_f32_32x32x16_f16 v[144:159], v[168:171], v[184:187], v[144:159]
	ds_read_b128 v[168:171], v12
	s_waitcnt lgkmcnt(3)
	v_mfma_f32_32x32x16_f16 v[144:159], v[172:175], v[188:191], v[144:159]
	ds_read_b128 v[172:175], v11
	s_waitcnt lgkmcnt(3)
	v_mfma_f32_32x32x16_f16 v[144:159], v[160:163], v[192:195], v[144:159]
	s_waitcnt lgkmcnt(2)
	v_mfma_f32_32x32x16_f16 v[144:159], v[164:167], v[196:199], v[144:159]
	s_waitcnt lgkmcnt(1)
	v_mfma_f32_32x32x16_f16 v[144:159], v[168:171], v[200:203], v[144:159]
	s_waitcnt lgkmcnt(0)
	v_mfma_f32_32x32x16_f16 v[144:159], v[172:175], v[204:207], v[144:159]
	s_cbranch_vccnz .LBB0_203
	v_add_u32_e32 v0, 27, v239
	v_cmp_lt_i32_e32 vcc, -1, v0
	v_mov_b32_e32 v161, 0xf149f2ca
	v_mov_b32_e32 v160, 0xf149f2ca
	s_and_saveexec_b64 s[22:23], vcc
	s_cbranch_execz .LBB0_172
	v_min_u32_e32 v0, 0x80, v0
	v_lshl_add_u32 v0, v0, 2, 0
	v_add_u32_e32 v0, 0x20000, v0
	ds_read_b32 v0, v0
	s_waitcnt lgkmcnt(0)
	v_add_f32_e32 v160, v144, v0

; #define LAS __attribute__((address_space(3)))
; __device__ __forceinline__ void attn_phase(LAS unsigned char* lds, const h16* Qb, const h16* Kb, const h16* Vt, h16* AO, const float* rel_bias, const float* lam, const float* subg, float lambda_init) {
;     ...
;                     if (64 * kt + 32 * kb <= q0 + 32 * rg + 31) {
;                         f32x16 S0;
; #pragma unroll
;                         for (int r = 0; r < 16; ++r) S0[r] = 0.f;
;                         LAS unsigned char* ks = cb + (32 * kb + l32) * 512 + mp * 256;
; #pragma unroll
;                         for (int k = 0; k < 8; ++k) {
;                             const h16x8 a0 = *(LAS h16x8*)(ks + (((2 * k + hh) ^ xk) << 4));
;                             S0 = __builtin_amdgcn_mfma_f32_32x32x16_f16(a0, Qf[k], S0, 0, 0, 0);
;                         }
;                         if (near) {
; #pragma unroll
;                             for (int r = 0; r < 16; ++r) {
;                                 const int kp = 64 * kt + 32 * kb + (r >> 2) * 8 + hh * 4 + (r & 3); const int d0 = qrow - kp;
;                                 const int di = d0 < 0 ? 0 : (d0 > 128 ? 128 : d0); const float bv = lut[di];
;                                 S0[r] = d0 < 0 ? -1e30f : S0[r] + bv;
;     ...
;                         float ps = 0.f;
; #pragma unroll
;                         for (int r = 0; r < 16; ++r) { S0[r] = __builtin_amdgcn_exp2f(S0[r] - mrun); ps += S0[r]; }
;                         lrun += ps;
;                         h16x8 P0, P1;
; #pragma unroll
;                         for (int e = 0; e < 8; ++e) { P0[e] = (h16)S0[e]; P1[e] = (h16)S0[8 + e]; }
;                         LAS unsigned char* vs = cb + 32768 + l32 * 128;
;                         const int vo0 = ((4 * kb + hh) ^ yv) << 4, vo1 = ((4 * kb + 2 + hh) ^ yv) << 4;
; #pragma unroll
;                         for (int dvb = 0; dvb < 8; ++dvb) {
;                             const h16x8 a = *(LAS h16x8*)(vs + dvb * 4096 + vo0);
;                             O[dvb] = __builtin_amdgcn_mfma_f32_32x32x16_f16(a, P0, O[dvb], 0, 0, 0);
;                         }
; #pragma unroll
;                         for (int dvb = 0; dvb < 8; ++dvb) {
;                             const h16x8 a = *(LAS h16x8*)(vs + dvb * 4096 + vo1);
;                             O[dvb] = __builtin_amdgcn_mfma_f32_32x32x16_f16(a, P1, O[dvb], 0, 0, 0);
;                         }
.LBB0_205:
	v_sub_f32_e32 v0, v144, v250
	v_exp_f32_e32 v0, v0
	v_sub_f32_e32 v3, v145, v250
	v_exp_f32_e32 v3, v3
	v_sub_f32_e32 v4, v146, v250
	v_exp_f32_e32 v4, v4
	v_sub_f32_e32 v5, v147, v250
	v_exp_f32_e32 v5, v5
	v_sub_f32_e32 v6, v148, v250
	v_add_f32_e32 v2, 0, v0
	v_exp_f32_e32 v6, v6
	v_sub_f32_e32 v7, v149, v250
	v_add_f32_e32 v2, v3, v2
	v_exp_f32_e32 v7, v7
	v_sub_f32_e32 v8, v150, v250
	v_add_f32_e32 v2, v4, v2
	v_exp_f32_e32 v8, v8
	v_sub_f32_e32 v9, v151, v250
	v_add_f32_e32 v2, v5, v2
	v_exp_f32_e32 v9, v9
	v_sub_f32_e32 v144, v152, v250
	v_add_f32_e32 v2, v6, v2
	v_exp_f32_e32 v144, v144
	v_sub_f32_e32 v145, v153, v250
	v_add_f32_e32 v2, v7, v2
	v_exp_f32_e32 v145, v145
	v_sub_f32_e32 v146, v154, v250
	v_add_f32_e32 v2, v8, v2
	v_exp_f32_e32 v146, v146
	v_sub_f32_e32 v147, v155, v250
	v_add_f32_e32 v2, v9, v2
	v_exp_f32_e32 v147, v147
	v_sub_f32_e32 v148, v156, v250
	v_add_f32_e32 v2, v144, v2
	v_exp_f32_e32 v148, v148
	v_sub_f32_e32 v149, v157, v250
	v_add_f32_e32 v2, v145, v2
	v_exp_f32_e32 v149, v149
	v_sub_f32_e32 v150, v158, v250
	v_add_f32_e32 v2, v146, v2
	v_exp_f32_e32 v150, v150
	v_sub_f32_e32 v151, v159, v250
	v_add_f32_e32 v2, v147, v2
	v_exp_f32_e32 v151, v151
	v_add_f32_e32 v2, v148, v2
	v_add_f32_e32 v2, v149, v2
	v_add_f32_e32 v2, v150, v2
	v_cvt_pk_f16_f32 v9, v8, v9
	v_cvt_pk_f16_f32 v8, v6, v7
	v_cvt_pk_f16_f32 v6, v0, v3
	v_add_u32_e32 v0, v10, v235
	v_add_f32_e32 v152, v151, v2
	v_cvt_pk_f16_f32 v3, v146, v147
	v_cvt_pk_f16_f32 v2, v144, v145
	v_cvt_pk_f16_f32 v7, v4, v5
	v_cvt_pk_f16_f32 v5, v150, v151
	v_cvt_pk_f16_f32 v4, v148, v149
	v_add_f32_e32 v224, v224, v152
	v_add_u32_e32 v153, v10, v236
	s_nop 0
	ds_read_b128 v[160:163], v0 offset:32768
	ds_read_b128 v[164:167], v0 offset:36864
	ds_read_b128 v[168:171], v0 offset:40960
	ds_read_b128 v[172:175], v0 offset:45056
	s_waitcnt lgkmcnt(3)
	v_mfma_f32_32x32x16_f16 v[128:143], v[160:163], v[6:9], v[128:143]
	ds_read_b128 v[160:163], v0 offset:49152
	s_waitcnt lgkmcnt(3)
	v_mfma_f32_32x32x16_f16 v[112:127], v[164:167], v[6:9], v[112:127]
	ds_read_b128 v[164:167], v0 offset:53248
	s_waitcnt lgkmcnt(3)
	v_mfma_f32_32x32x16_f16 v[96:111], v[168:171], v[6:9], v[96:111]
	ds_read_b128 v[168:171], v0 offset:57344
	s_waitcnt lgkmcnt(3)
	v_mfma_f32_32x32x16_f16 v[80:95], v[172:175], v[6:9], v[80:95]
	ds_read_b128 v[172:175], v0 offset:61440
	s_waitcnt lgkmcnt(3)
	v_mfma_f32_32x32x16_f16 v[64:79], v[160:163], v[6:9], v[64:79]
	ds_read_b128 v[160:163], v153 offset:32768
	s_waitcnt lgkmcnt(3)
	v_mfma_f32_32x32x16_f16 v[48:63], v[164:167], v[6:9], v[48:63]
	ds_read_b128 v[164:167], v153 offset:36864
	s_waitcnt lgkmcnt(3)
	v_mfma_f32_32x32x16_f16 v[32:47], v[168:171], v[6:9], v[32:47]
	ds_read_b128 v[168:171], v153 offset:40960
	s_waitcnt lgkmcnt(3)
	v_mfma_f32_32x32x16_f16 v[16:31], v[172:175], v[6:9], v[16:31]
	ds_read_b128 v[172:175], v153 offset:45056
	s_waitcnt lgkmcnt(3)
	v_mfma_f32_32x32x16_f16 v[128:143], v[160:163], v[2:5], v[128:143]
	ds_read_b128 v[160:163], v153 offset:49152
	s_waitcnt lgkmcnt(3)
	v_mfma_f32_32x32x16_f16 v[112:127], v[164:167], v[2:5], v[112:127]
	ds_read_b128 v[164:167], v153 offset:53248
	s_waitcnt lgkmcnt(3)
	v_mfma_f32_32x32x16_f16 v[96:111], v[168:171], v[2:5], v[96:111]
	ds_read_b128 v[168:171], v153 offset:57344
	s_waitcnt lgkmcnt(3)
	v_mfma_f32_32x32x16_f16 v[80:95], v[172:175], v[2:5], v[80:95]
	ds_read_b128 v[172:175], v153 offset:61440
	s_waitcnt lgkmcnt(3)
	v_mfma_f32_32x32x16_f16 v[64:79], v[160:163], v[2:5], v[64:79]
	s_waitcnt lgkmcnt(2)
	v_mfma_f32_32x32x16_f16 v[48:63], v[164:167], v[2:5], v[48:63]
	s_waitcnt lgkmcnt(1)
	v_mfma_f32_32x32x16_f16 v[32:47], v[168:171], v[2:5], v[32:47]
	s_waitcnt lgkmcnt(0)
	v_mfma_f32_32x32x16_f16 v[16:31], v[172:175], v[2:5], v[16:31]
.LBB0_206:
	s_add_i32 s20, s50, 32
	s_cmp_gt_i32 s20, s48
	s_cbranch_scc1 .LBB0_244
	ds_read_b128 v[160:163], v213 offset:16384
	ds_read_b128 v[164:167], v212 offset:16384
	ds_read_b128 v[168:171], v245 offset:16384
	ds_read_b128 v[172:175], v15 offset:16384
	s_and_b64 vcc, exec, s[38:39]
	s_waitcnt lgkmcnt(3)
	v_mfma_f32_32x32x16_f16 v[144:159], v[160:163], v[176:179], 0
	ds_read_b128 v[160:163], v14 offset:16384
	s_waitcnt lgkmcnt(3)
	v_mfma_f32_32x32x16_f16 v[144:159], v[164:167], v[180:183], v[144:159]
	ds_read_b128 v[164:167], v13 offset:16384
	s_waitcnt lgkmcnt(3)
	v_mfma_f32_32x32x16_f16 v[144:159], v[168:171], v[184:187], v[144:159]
	ds_read_b128 v[168:171], v12 offset:16384
	s_waitcnt lgkmcnt(3)
	v_mfma_f32_32x32x16_f16 v[144:159], v[172:175], v[188:191], v[144:159]
	ds_read_b128 v[172:175], v11 offset:16384
	s_waitcnt lgkmcnt(3)
	v_mfma_f32_32x32x16_f16 v[144:159], v[160:163], v[192:195], v[144:159]
	s_waitcnt lgkmcnt(2)
	v_mfma_f32_32x32x16_f16 v[144:159], v[164:167], v[196:199], v[144:159]
	s_waitcnt lgkmcnt(1)
	v_mfma_f32_32x32x16_f16 v[144:159], v[168:171], v[200:203], v[144:159]
	s_waitcnt lgkmcnt(0)
	v_mfma_f32_32x32x16_f16 v[144:159], v[172:175], v[204:207], v[144:159]
	s_cbranch_vccnz .LBB0_241
	v_add_u32_e32 v0, -5, v239
	v_cmp_lt_i32_e32 vcc, -1, v0
	v_mov_b32_e32 v161, 0xf149f2ca
	v_mov_b32_e32 v160, 0xf149f2ca
	s_and_saveexec_b64 s[22:23], vcc
	s_cbranch_execz .LBB0_210
	v_min_u32_e32 v0, 0x80, v0
	v_lshl_add_u32 v0, v0, 2, 0
	v_add_u32_e32 v0, 0x20000, v0
	ds_read_b32 v0, v0
	s_waitcnt lgkmcnt(0)
	v_add_f32_e32 v160, v144, v0

; #define LAS __attribute__((address_space(3)))
; __device__ __forceinline__ void attn_phase(LAS unsigned char* lds, const h16* Qb, const h16* Kb, const h16* Vt, h16* AO, const float* rel_bias, const float* lam, const float* subg, float lambda_init) {
;     ...
;                         float ps = 0.f;
; #pragma unroll
;                         for (int r = 0; r < 16; ++r) { S0[r] = __builtin_amdgcn_exp2f(S0[r] - mrun); ps += S0[r]; }
;                         lrun += ps;
;                         h16x8 P0, P1;
; #pragma unroll
;                         for (int e = 0; e < 8; ++e) { P0[e] = (h16)S0[e]; P1[e] = (h16)S0[8 + e]; }
;                         LAS unsigned char* vs = cb + 32768 + l32 * 128;
;                         const int vo0 = ((4 * kb + hh) ^ yv) << 4, vo1 = ((4 * kb + 2 + hh) ^ yv) << 4;
; #pragma unroll
;                         for (int dvb = 0; dvb < 8; ++dvb) {
;                             const h16x8 a = *(LAS h16x8*)(vs + dvb * 4096 + vo0);
;                             O[dvb] = __builtin_amdgcn_mfma_f32_32x32x16_f16(a, P0, O[dvb], 0, 0, 0);
;                         }
; #pragma unroll
;                         for (int dvb = 0; dvb < 8; ++dvb) {
;                             const h16x8 a = *(LAS h16x8*)(vs + dvb * 4096 + vo1);
;                             O[dvb] = __builtin_amdgcn_mfma_f32_32x32x16_f16(a, P1, O[dvb], 0, 0, 0);
;                         }
.LBB0_243:
	v_sub_f32_e32 v0, v144, v250
	v_exp_f32_e32 v0, v0
	v_sub_f32_e32 v3, v145, v250
	v_exp_f32_e32 v3, v3
	v_sub_f32_e32 v4, v146, v250
	v_exp_f32_e32 v4, v4
	v_sub_f32_e32 v5, v147, v250
	v_exp_f32_e32 v5, v5
	v_sub_f32_e32 v6, v148, v250
	v_add_f32_e32 v2, 0, v0
	v_exp_f32_e32 v6, v6
	v_sub_f32_e32 v7, v149, v250
	v_add_f32_e32 v2, v3, v2
	v_exp_f32_e32 v7, v7
	v_sub_f32_e32 v8, v150, v250
	v_add_f32_e32 v2, v4, v2
	v_exp_f32_e32 v8, v8
	v_sub_f32_e32 v9, v151, v250
	v_add_f32_e32 v2, v5, v2
	v_exp_f32_e32 v9, v9
	v_sub_f32_e32 v11, v152, v250
	v_add_f32_e32 v2, v6, v2
	v_exp_f32_e32 v11, v11
	v_sub_f32_e32 v12, v153, v250
	v_add_f32_e32 v2, v7, v2
	v_exp_f32_e32 v12, v12
	v_sub_f32_e32 v13, v154, v250
	v_add_f32_e32 v2, v8, v2
	v_exp_f32_e32 v13, v13
	v_sub_f32_e32 v14, v155, v250
	v_add_f32_e32 v2, v9, v2
	v_exp_f32_e32 v14, v14
	v_sub_f32_e32 v15, v156, v250
	v_add_f32_e32 v2, v11, v2
	v_exp_f32_e32 v15, v15
	v_sub_f32_e32 v144, v157, v250
	v_add_f32_e32 v2, v12, v2
	v_exp_f32_e32 v144, v144
	v_sub_f32_e32 v145, v158, v250
	v_add_f32_e32 v2, v13, v2
	v_exp_f32_e32 v145, v145
	v_sub_f32_e32 v146, v159, v250
	v_add_f32_e32 v2, v14, v2
	v_exp_f32_e32 v146, v146
	v_add_f32_e32 v2, v15, v2
	v_add_f32_e32 v2, v144, v2
	v_add_f32_e32 v2, v145, v2
	v_cvt_pk_f16_f32 v9, v8, v9
	v_cvt_pk_f16_f32 v8, v6, v7
	v_cvt_pk_f16_f32 v6, v0, v3
	v_add_u32_e32 v0, v10, v237
	v_add_f32_e32 v147, v146, v2
	v_cvt_pk_f16_f32 v7, v4, v5
	v_cvt_pk_f16_f32 v4, v15, v144
	v_cvt_pk_f16_f32 v3, v13, v14
	v_cvt_pk_f16_f32 v2, v11, v12
	v_cvt_pk_f16_f32 v5, v145, v146
	v_add_f32_e32 v224, v224, v147
	v_add_u32_e32 v153, v10, v238
	s_nop 0
	ds_read_b128 v[160:163], v0 offset:32768
	ds_read_b128 v[164:167], v0 offset:36864
	ds_read_b128 v[168:171], v0 offset:40960
	ds_read_b128 v[172:175], v0 offset:45056
	s_waitcnt lgkmcnt(3)
	v_mfma_f32_32x32x16_f16 v[128:143], v[160:163], v[6:9], v[128:143]
	ds_read_b128 v[160:163], v0 offset:49152
	s_waitcnt lgkmcnt(3)
	v_mfma_f32_32x32x16_f16 v[112:127], v[164:167], v[6:9], v[112:127]
	ds_read_b128 v[164:167], v0 offset:53248
	s_waitcnt lgkmcnt(3)
	v_mfma_f32_32x32x16_f16 v[96:111], v[168:171], v[6:9], v[96:111]
	ds_read_b128 v[168:171], v0 offset:57344
	s_waitcnt lgkmcnt(3)
	v_mfma_f32_32x32x16_f16 v[80:95], v[172:175], v[6:9], v[80:95]
	ds_read_b128 v[172:175], v0 offset:61440
	s_waitcnt lgkmcnt(3)
	v_mfma_f32_32x32x16_f16 v[64:79], v[160:163], v[6:9], v[64:79]
	ds_read_b128 v[160:163], v153 offset:32768
	s_waitcnt lgkmcnt(3)
	v_mfma_f32_32x32x16_f16 v[48:63], v[164:167], v[6:9], v[48:63]
	ds_read_b128 v[164:167], v153 offset:36864
	s_waitcnt lgkmcnt(3)
	v_mfma_f32_32x32x16_f16 v[32:47], v[168:171], v[6:9], v[32:47]
	ds_read_b128 v[168:171], v153 offset:40960
	s_waitcnt lgkmcnt(3)
	v_mfma_f32_32x32x16_f16 v[16:31], v[172:175], v[6:9], v[16:31]
	ds_read_b128 v[172:175], v153 offset:45056
	s_waitcnt lgkmcnt(3)
	v_mfma_f32_32x32x16_f16 v[128:143], v[160:163], v[2:5], v[128:143]
	ds_read_b128 v[160:163], v153 offset:49152
	s_waitcnt lgkmcnt(3)
	v_mfma_f32_32x32x16_f16 v[112:127], v[164:167], v[2:5], v[112:127]
	ds_read_b128 v[164:167], v153 offset:53248
	s_waitcnt lgkmcnt(3)
	v_mfma_f32_32x32x16_f16 v[96:111], v[168:171], v[2:5], v[96:111]
	ds_read_b128 v[168:171], v153 offset:57344
	s_waitcnt lgkmcnt(3)
	v_mfma_f32_32x32x16_f16 v[80:95], v[172:175], v[2:5], v[80:95]
	ds_read_b128 v[172:175], v153 offset:61440
	s_waitcnt lgkmcnt(3)
	v_mfma_f32_32x32x16_f16 v[64:79], v[160:163], v[2:5], v[64:79]
	s_waitcnt lgkmcnt(2)
	v_mfma_f32_32x32x16_f16 v[48:63], v[164:167], v[2:5], v[48:63]
	s_waitcnt lgkmcnt(1)
	v_mfma_f32_32x32x16_f16 v[32:47], v[168:171], v[2:5], v[32:47]
	s_waitcnt lgkmcnt(0)
	v_mfma_f32_32x32x16_f16 v[16:31], v[172:175], v[2:5], v[16:31]

; __device__ __forceinline__ void scan_phase(LAS unsigned char* lds, const h16* C1, const h16* DEC, const h16* AA, const h16* BB, float* Y, ...
;     ...
;             const int jg = lane & 15, rl = wid * 4 + (lane >> 4);
;             f32x2 Sa = (f32x2){0.f, 0.f}, Sb = (f32x2){0.f, 0.f};
;             float sa = 0.f;
;             __syncthreads();
;             for (int c = 0; c < NCH; ++c) {
;                 LAS float* Bf = L + (c & 1) * BUF;
;                 LAS float* vec = Bf + jg * 4;
;                 f32x4 r4 = *(LAS f32x4*)(vec + 0 * 2048), w4 = *(LAS f32x4*)(vec + 1 * 2048), k4 = *(LAS f32x4*)(vec + 2 * 2048), a4 = *(LAS f32x4*)(vec + 3 * 2048), b4 = *(LAS f32x4*)(vec + 4 * 2048);
;                 float v = Bf[10240 + rl], cn = Bf[18944];
; #pragma unroll 1
;                 for (int s0 = 0; s0 < CH; s0 += 8) {
;                     float yv[8];
; #pragma unroll
;                     for (int u = 0; u < 8; ++u) {
;                         const int s = s0 + u, sn = (s + 1 < CH) ? s + 1 : CH - 1;
;                         const f32x4 r4n = *(LAS f32x4*)(vec + 0 * 2048 + sn * 64), w4n = *(LAS f32x4*)(vec + 1 * 2048 + sn * 64), k4n = *(LAS f32x4*)(vec + 2 * 2048 + sn * 64),
;                                     a4n = *(LAS f32x4*)(vec + 3 * 2048 + sn * 64), b4n = *(LAS f32x4*)(vec + 4 * 2048 + sn * 64);
;                         const float vn = Bf[10240 + sn * 16 + rl], cnn = Bf[18944 + sn];
;                         const f32x2 aL = {a4[0], a4[1]}, aH = {a4[2], a4[3]}, wL = {w4[0], w4[1]}, wH = {w4[2], w4[3]}, kL = {k4[0], k4[1]}, kH = {k4[2], k4[3]},
;                                     bL = {b4[0], b4[1]}, bH = {b4[2], b4[3]}, rL = {r4[0], r4[1]}, rH = {r4[2], r4[3]};
;                         const f32x2 uL = Sa * wL + kL * v, uH = Sb * wH + kH * v;
;                         const f32x2 dz = uL * aL + uH * aH;
;                         const float z = row16_sum(dz[0] + dz[1]);
;                         Sa = bL * sa + uL; Sb = bH * sa + uH;
;                         const f32x2 dr = Sa * rL + Sb * rH;
;                         yv[u] = dr[0] + dr[1];
;                         sa = z + cn * sa;
;                         r4 = r4n; w4 = w4n; k4 = k4n; a4 = a4n; b4 = b4n; v = vn; cn = cnn;
;                     }
; #pragma unroll
;                     for (int u = 0; u < 8; ++u) Bf[10752 + ((s0 + u) * 16 + rl) * 16 + jg] = yv[u];
.LBB0_413:
	s_waitcnt vmcnt(0) lgkmcnt(0)
	s_barrier
	s_and_saveexec_b64 s[20:21], s[38:39]
	s_xor_b64 s[22:23], exec, s[20:21]
	s_cbranch_execz .LBB0_418
	s_mov_b32 s24, 0
	v_mov_b32_e32 v108, 0
	v_mov_b32_e32 v109, 0
	v_mov_b32_e32 v110, 0
	v_mov_b32_e32 v111, 0
	v_mov_b32_e32 v112, 0
	v_mov_b32_e32 v113, 0
	s_barrier
.Lscan_chunk:
	s_bitcmp1_b32 s24, 0
	s_cselect_b32 s26, 0x12880, 0
	v_add_u32_e32 v0, s26, v65
	v_lshl_add_u32 v97, v61, 2, s26
	s_add_i32 s20, s26, 0x12800
	v_add_u32_e32 v158, s26, v149
	v_add_u32_e32 v97, 0xa000, v97
	v_mov_b32_e32 v157, s20
	v_add_u32_e32 v156, 0x400, v97
	ds_read_b128 v[4:7], v0 offset:16384
	ds_read_b128 v[12:15], v0 offset:24576
	ds_read_b128 v[8:11], v0 offset:8192
	ds_read2_b32 v[56:57], v97 offset0:0 offset1:16
	ds_read_b128 v[16:19], v0 offset:16640
	ds_read_b128 v[24:27], v0 offset:24832
	ds_read_b128 v[20:23], v0 offset:8448
	ds_read_b128 v[44:47], v0 offset:32768
	ds_read_b128 v[40:43], v0 offset:0
	ds_read2_b32 v[154:155], v157 offset0:0 offset1:1
	ds_read_b128 v[28:31], v0 offset:16896
	ds_read_b128 v[36:39], v0 offset:25088
	ds_read_b128 v[32:35], v0 offset:8704
	ds_read_b128 v[52:55], v0 offset:33024
	ds_read_b128 v[48:51], v0 offset:256
	s_waitcnt lgkmcnt(11)
	ds_read2_b32 v[98:99], v97 offset0:32 offset1:48
	v_pk_mul_f32 v[4:5], v[4:5], v[56:57] op_sel_hi:[1,0]
	v_pk_mul_f32 v[6:7], v[6:7], v[56:57] op_sel_hi:[1,0]
	v_pk_fma_f32 v[8:9], v[108:109], v[8:9], v[4:5]
	v_pk_fma_f32 v[10:11], v[110:111], v[10:11], v[6:7]
	v_pk_mul_f32 v[12:13], v[12:13], v[8:9]
	v_pk_fma_f32 v[12:13], v[14:15], v[10:11], v[12:13]
	v_add_f32_e32 v112, v12, v13
	s_waitcnt lgkmcnt(6)
	ds_read_b128 v[4:7], v0 offset:17152
	ds_read_b128 v[12:15], v0 offset:25344
	ds_read_b128 v[104:107], v0 offset:33280
	ds_read_b128 v[100:103], v0 offset:512
	ds_read2_b32 v[160:161], v157 offset0:2 offset1:3
	v_pk_fma_f32 v[108:109], v[44:45], v[112:113], v[8:9] op_sel:[0,1,0] op_sel_hi:[1,1,1]
	v_pk_fma_f32 v[110:111], v[46:47], v[112:113], v[10:11] op_sel:[0,1,0] op_sel_hi:[1,1,1]
	ds_read_b128 v[8:11], v0 offset:8960
	v_add_f32_dpp v112, v112, v112 quad_perm:[1,0,3,2] row_mask:0xf bank_mask:0xf bound_ctrl:1
	v_pk_mul_f32 v[16:17], v[16:17], v[56:57] op_sel:[0,1] op_sel_hi:[1,1]
	v_pk_mul_f32 v[18:19], v[18:19], v[56:57] op_sel:[0,1] op_sel_hi:[1,1]
	v_pk_fma_f32 v[20:21], v[108:109], v[20:21], v[16:17]
	v_add_f32_dpp v112, v112, v112 quad_perm:[2,3,0,1] row_mask:0xf bank_mask:0xf bound_ctrl:1
	v_pk_fma_f32 v[22:23], v[110:111], v[22:23], v[18:19]
	v_pk_mul_f32 v[24:25], v[24:25], v[20:21]
	v_add_f32_dpp v112, v112, v112 row_half_mirror row_mask:0xf bank_mask:0xf bound_ctrl:1
	v_pk_mul_f32 v[40:41], v[40:41], v[108:109]
	v_pk_fma_f32 v[24:25], v[26:27], v[22:23], v[24:25]
	v_add_f32_dpp v112, v112, v112 row_mirror row_mask:0xf bank_mask:0xf bound_ctrl:1
	v_pk_fma_f32 v[40:41], v[42:43], v[110:111], v[40:41]
	v_fmac_f32_e32 v112, v154, v113
	v_add_f32_e32 v2, v40, v41
	v_add_f32_e32 v113, v24, v25
	s_waitcnt lgkmcnt(6)
	ds_read_b128 v[16:19], v0 offset:17408
	ds_read_b128 v[24:27], v0 offset:25600
	ds_read_b128 v[44:47], v0 offset:33536
	ds_read_b128 v[40:43], v0 offset:768
	ds_read2_b32 v[56:57], v97 offset0:64 offset1:80
	v_pk_fma_f32 v[108:109], v[52:53], v[112:113], v[20:21] op_sel:[0,0,0] op_sel_hi:[1,0,1]
	v_pk_fma_f32 v[110:111], v[54:55], v[112:113], v[22:23] op_sel:[0,0,0] op_sel_hi:[1,0,1]
	ds_read_b128 v[20:23], v0 offset:9216
	v_add_f32_dpp v113, v113, v113 quad_perm:[1,0,3,2] row_mask:0xf bank_mask:0xf bound_ctrl:1
	v_pk_mul_f32 v[28:29], v[28:29], v[98:99] op_sel_hi:[1,0]
	v_pk_mul_f32 v[30:31], v[30:31], v[98:99] op_sel_hi:[1,0]
	v_pk_fma_f32 v[32:33], v[108:109], v[32:33], v[28:29]
	v_add_f32_dpp v113, v113, v113 quad_perm:[2,3,0,1] row_mask:0xf bank_mask:0xf bound_ctrl:1
	v_pk_fma_f32 v[34:35], v[110:111], v[34:35], v[30:31]
	v_pk_mul_f32 v[36:37], v[36:37], v[32:33]
	v_add_f32_dpp v113, v113, v113 row_half_mirror row_mask:0xf bank_mask:0xf bound_ctrl:1
	v_pk_mul_f32 v[48:49], v[48:49], v[108:109]
	v_pk_fma_f32 v[36:37], v[38:39], v[34:35], v[36:37]
	v_add_f32_dpp v113, v113, v113 row_mirror row_mask:0xf bank_mask:0xf bound_ctrl:1
	v_pk_fma_f32 v[48:49], v[50:51], v[110:111], v[48:49]
	v_fmac_f32_e32 v113, v155, v112
	v_add_f32_e32 v3, v48, v49
	v_add_f32_e32 v112, v36, v37
	ds_write2st64_b32 v158, v2, v3 offset0:0 offset1:4
	s_waitcnt lgkmcnt(7)
	ds_read_b128 v[28:31], v0 offset:17664
	ds_read_b128 v[36:39], v0 offset:25856
	ds_read_b128 v[52:55], v0 offset:33792
	ds_read_b128 v[48:51], v0 offset:1024
	ds_read2_b32 v[154:155], v157 offset0:4 offset1:5
	v_pk_fma_f32 v[108:109], v[104:105], v[112:113], v[32:33] op_sel:[0,1,0] op_sel_hi:[1,1,1]
	v_pk_fma_f32 v[110:111], v[106:107], v[112:113], v[34:35] op_sel:[0,1,0] op_sel_hi:[1,1,1]
	ds_read_b128 v[32:35], v0 offset:9472
	v_add_f32_dpp v112, v112, v112 quad_perm:[1,0,3,2] row_mask:0xf bank_mask:0xf bound_ctrl:1
	v_pk_mul_f32 v[4:5], v[4:5], v[98:99] op_sel:[0,1] op_sel_hi:[1,1]
	v_pk_mul_f32 v[6:7], v[6:7], v[98:99] op_sel:[0,1] op_sel_hi:[1,1]
	v_pk_fma_f32 v[8:9], v[108:109], v[8:9], v[4:5]
	v_add_f32_dpp v112, v112, v112 quad_perm:[2,3,0,1] row_mask:0xf bank_mask:0xf bound_ctrl:1
	v_pk_fma_f32 v[10:11], v[110:111], v[10:11], v[6:7]
	v_pk_mul_f32 v[12:13], v[12:13], v[8:9]
	v_add_f32_dpp v112, v112, v112 row_half_mirror row_mask:0xf bank_mask:0xf bound_ctrl:1
	v_pk_mul_f32 v[100:101], v[100:101], v[108:109]
	v_pk_fma_f32 v[12:13], v[14:15], v[10:11], v[12:13]
	v_add_f32_dpp v112, v112, v112 row_mirror row_mask:0xf bank_mask:0xf bound_ctrl:1
	v_pk_fma_f32 v[100:101], v[102:103], v[110:111], v[100:101]
	v_fmac_f32_e32 v112, v160, v113
	v_add_f32_e32 v2, v100, v101
	v_add_f32_e32 v113, v12, v13
	s_waitcnt lgkmcnt(7)
; #define LAS __attribute__((address_space(3)))
; __device__ __forceinline__ float row16_sum(float x) { x += dpp_f<0xB1>(x); x += dpp_f<0x4E>(x); x += dpp_f<0x141>(x); x += dpp_f<0x140>(x); return x; }
; __device__ __forceinline__ void scan_phase(LAS unsigned char* lds, const h16* C1, const h16* DEC, const h16* AA, const h16* BB, float* Y, ...
;     ...
;                 for (int s0 = 0; s0 < CH; s0 += 8) {
;                     float yv[8];
; #pragma unroll
;                     for (int u = 0; u < 8; ++u) {
;                         const int s = s0 + u, sn = (s + 1 < CH) ? s + 1 : CH - 1;
;                         const f32x4 r4n = *(LAS f32x4*)(vec + 0 * 2048 + sn * 64), w4n = *(LAS f32x4*)(vec + 1 * 2048 + sn * 64), k4n = *(LAS f32x4*)(vec + 2 * 2048 + sn * 64),
;                                     a4n = *(LAS f32x4*)(vec + 3 * 2048 + sn * 64), b4n = *(LAS f32x4*)(vec + 4 * 2048 + sn * 64);
;                         const float vn = Bf[10240 + sn * 16 + rl], cnn = Bf[18944 + sn];
;                         const f32x2 aL = {a4[0], a4[1]}, aH = {a4[2], a4[3]}, wL = {w4[0], w4[1]}, wH = {w4[2], w4[3]}, kL = {k4[0], k4[1]}, kH = {k4[2], k4[3]},
;                                     bL = {b4[0], b4[1]}, bH = {b4[2], b4[3]}, rL = {r4[0], r4[1]}, rH = {r4[2], r4[3]};
;                         const f32x2 uL = Sa * wL + kL * v, uH = Sb * wH + kH * v;
;                         const f32x2 dz = uL * aL + uH * aH;
;                         const float z = row16_sum(dz[0] + dz[1]);
;                         Sa = bL * sa + uL; Sb = bH * sa + uH;
;                         const f32x2 dr = Sa * rL + Sb * rH;
;                         yv[u] = dr[0] + dr[1];
;                         sa = z + cn * sa;
;                         r4 = r4n; w4 = w4n; k4 = k4n; a4 = a4n; b4 = b4n; v = vn; cn = cnn;
;                     }
; #pragma unroll
;                     for (int u = 0; u < 8; ++u) Bf[10752 + ((s0 + u) * 16 + rl) * 16 + jg] = yv[u];
	ds_read_b128 v[4:7], v0 offset:17920
	ds_read_b128 v[12:15], v0 offset:26112
	ds_read_b128 v[104:107], v0 offset:34048
	ds_read_b128 v[100:103], v0 offset:1280
	ds_read2_b32 v[98:99], v97 offset0:96 offset1:112
	v_pk_fma_f32 v[108:109], v[44:45], v[112:113], v[8:9] op_sel:[0,0,0] op_sel_hi:[1,0,1]
	v_pk_fma_f32 v[110:111], v[46:47], v[112:113], v[10:11] op_sel:[0,0,0] op_sel_hi:[1,0,1]
	ds_read_b128 v[8:11], v0 offset:9728
	v_add_f32_dpp v113, v113, v113 quad_perm:[1,0,3,2] row_mask:0xf bank_mask:0xf bound_ctrl:1
	v_pk_mul_f32 v[16:17], v[16:17], v[56:57] op_sel_hi:[1,0]
	v_pk_mul_f32 v[18:19], v[18:19], v[56:57] op_sel_hi:[1,0]
	v_pk_fma_f32 v[20:21], v[108:109], v[20:21], v[16:17]
	v_add_f32_dpp v113, v113, v113 quad_perm:[2,3,0,1] row_mask:0xf bank_mask:0xf bound_ctrl:1
	v_pk_fma_f32 v[22:23], v[110:111], v[22:23], v[18:19]
	v_pk_mul_f32 v[24:25], v[24:25], v[20:21]
	v_add_f32_dpp v113, v113, v113 row_half_mirror row_mask:0xf bank_mask:0xf bound_ctrl:1
	v_pk_mul_f32 v[40:41], v[40:41], v[108:109]
	v_pk_fma_f32 v[24:25], v[26:27], v[22:23], v[24:25]
	v_add_f32_dpp v113, v113, v113 row_mirror row_mask:0xf bank_mask:0xf bound_ctrl:1
	v_pk_fma_f32 v[40:41], v[42:43], v[110:111], v[40:41]
	v_fmac_f32_e32 v113, v161, v112
	v_add_f32_e32 v3, v40, v41
	v_add_f32_e32 v112, v24, v25
	ds_write2st64_b32 v158, v2, v3 offset0:8 offset1:12
	s_waitcnt lgkmcnt(7)
	ds_read_b128 v[16:19], v0 offset:18176
	ds_read_b128 v[24:27], v0 offset:26368
	ds_read_b128 v[44:47], v0 offset:34304
	ds_read_b128 v[40:43], v0 offset:1536
	ds_read2_b32 v[160:161], v157 offset0:6 offset1:7
	v_pk_fma_f32 v[108:109], v[52:53], v[112:113], v[20:21] op_sel:[0,1,0] op_sel_hi:[1,1,1]
	v_pk_fma_f32 v[110:111], v[54:55], v[112:113], v[22:23] op_sel:[0,1,0] op_sel_hi:[1,1,1]
	ds_read_b128 v[20:23], v0 offset:9984
	v_add_f32_dpp v112, v112, v112 quad_perm:[1,0,3,2] row_mask:0xf bank_mask:0xf bound_ctrl:1
	v_pk_mul_f32 v[28:29], v[28:29], v[56:57] op_sel:[0,1] op_sel_hi:[1,1]
	v_pk_mul_f32 v[30:31], v[30:31], v[56:57] op_sel:[0,1] op_sel_hi:[1,1]
	v_pk_fma_f32 v[32:33], v[108:109], v[32:33], v[28:29]
	v_add_f32_dpp v112, v112, v112 quad_perm:[2,3,0,1] row_mask:0xf bank_mask:0xf bound_ctrl:1
	v_pk_fma_f32 v[34:35], v[110:111], v[34:35], v[30:31]
	v_pk_mul_f32 v[36:37], v[36:37], v[32:33]
	v_add_f32_dpp v112, v112, v112 row_half_mirror row_mask:0xf bank_mask:0xf bound_ctrl:1
	v_pk_mul_f32 v[48:49], v[48:49], v[108:109]
	v_pk_fma_f32 v[36:37], v[38:39], v[34:35], v[36:37]
	v_add_f32_dpp v112, v112, v112 row_mirror row_mask:0xf bank_mask:0xf bound_ctrl:1
	v_pk_fma_f32 v[48:49], v[50:51], v[110:111], v[48:49]
	v_fmac_f32_e32 v112, v154, v113
	v_add_f32_e32 v2, v48, v49
	v_add_f32_e32 v113, v36, v37
	s_waitcnt lgkmcnt(7)
	ds_read_b128 v[28:31], v0 offset:18432
	ds_read_b128 v[36:39], v0 offset:26624
	ds_read_b128 v[52:55], v0 offset:34560
	ds_read_b128 v[48:51], v0 offset:1792
	ds_read2_b32 v[56:57], v97 offset0:128 offset1:144
	v_pk_fma_f32 v[108:109], v[104:105], v[112:113], v[32:33] op_sel:[0,0,0] op_sel_hi:[1,0,1]
	v_pk_fma_f32 v[110:111], v[106:107], v[112:113], v[34:35] op_sel:[0,0,0] op_sel_hi:[1,0,1]
	ds_read_b128 v[32:35], v0 offset:10240
	v_add_f32_dpp v113, v113, v113 quad_perm:[1,0,3,2] row_mask:0xf bank_mask:0xf bound_ctrl:1
	v_pk_mul_f32 v[4:5], v[4:5], v[98:99] op_sel_hi:[1,0]
	v_pk_mul_f32 v[6:7], v[6:7], v[98:99] op_sel_hi:[1,0]
	v_pk_fma_f32 v[8:9], v[108:109], v[8:9], v[4:5]
	v_add_f32_dpp v113, v113, v113 quad_perm:[2,3,0,1] row_mask:0xf bank_mask:0xf bound_ctrl:1
	v_pk_fma_f32 v[10:11], v[110:111], v[10:11], v[6:7]
	v_pk_mul_f32 v[12:13], v[12:13], v[8:9]
	v_add_f32_dpp v113, v113, v113 row_half_mirror row_mask:0xf bank_mask:0xf bound_ctrl:1
	v_pk_mul_f32 v[100:101], v[100:101], v[108:109]
	v_pk_fma_f32 v[12:13], v[14:15], v[10:11], v[12:13]
	v_add_f32_dpp v113, v113, v113 row_mirror row_mask:0xf bank_mask:0xf bound_ctrl:1
	v_pk_fma_f32 v[100:101], v[102:103], v[110:111], v[100:101]
	v_fmac_f32_e32 v113, v155, v112
	v_add_f32_e32 v3, v100, v101
	v_add_f32_e32 v112, v12, v13
	ds_write2st64_b32 v158, v2, v3 offset0:16 offset1:20
	s_waitcnt lgkmcnt(7)
	ds_read_b128 v[4:7], v0 offset:18688
	ds_read_b128 v[12:15], v0 offset:26880
	ds_read_b128 v[104:107], v0 offset:34816
	ds_read_b128 v[100:103], v0 offset:2048
	ds_read2_b32 v[154:155], v157 offset0:8 offset1:9
	v_pk_fma_f32 v[108:109], v[44:45], v[112:113], v[8:9] op_sel:[0,1,0] op_sel_hi:[1,1,1]
	v_pk_fma_f32 v[110:111], v[46:47], v[112:113], v[10:11] op_sel:[0,1,0] op_sel_hi:[1,1,1]
	ds_read_b128 v[8:11], v0 offset:10496
	v_add_f32_dpp v112, v112, v112 quad_perm:[1,0,3,2] row_mask:0xf bank_mask:0xf bound_ctrl:1
	v_pk_mul_f32 v[16:17], v[16:17], v[98:99] op_sel:[0,1] op_sel_hi:[1,1]
	v_pk_mul_f32 v[18:19], v[18:19], v[98:99] op_sel:[0,1] op_sel_hi:[1,1]
	v_pk_fma_f32 v[20:21], v[108:109], v[20:21], v[16:17]
	v_add_f32_dpp v112, v112, v112 quad_perm:[2,3,0,1] row_mask:0xf bank_mask:0xf bound_ctrl:1
	v_pk_fma_f32 v[22:23], v[110:111], v[22:23], v[18:19]
	v_pk_mul_f32 v[24:25], v[24:25], v[20:21]
	v_add_f32_dpp v112, v112, v112 row_half_mirror row_mask:0xf bank_mask:0xf bound_ctrl:1
	v_pk_mul_f32 v[40:41], v[40:41], v[108:109]
	v_pk_fma_f32 v[24:25], v[26:27], v[22:23], v[24:25]
	v_add_f32_dpp v112, v112, v112 row_mirror row_mask:0xf bank_mask:0xf bound_ctrl:1
	v_pk_fma_f32 v[40:41], v[42:43], v[110:111], v[40:41]
	v_fmac_f32_e32 v112, v160, v113
	v_add_f32_e32 v2, v40, v41
	v_add_f32_e32 v113, v24, v25
	s_waitcnt lgkmcnt(7)
; #define LAS __attribute__((address_space(3)))
; __device__ __forceinline__ float row16_sum(float x) { x += dpp_f<0xB1>(x); x += dpp_f<0x4E>(x); x += dpp_f<0x141>(x); x += dpp_f<0x140>(x); return x; }
; __device__ __forceinline__ void scan_phase(LAS unsigned char* lds, const h16* C1, const h16* DEC, const h16* AA, const h16* BB, float* Y, ...
;     ...
;                 for (int s0 = 0; s0 < CH; s0 += 8) {
;                     float yv[8];
; #pragma unroll
;                     for (int u = 0; u < 8; ++u) {
;                         const int s = s0 + u, sn = (s + 1 < CH) ? s + 1 : CH - 1;
;                         const f32x4 r4n = *(LAS f32x4*)(vec + 0 * 2048 + sn * 64), w4n = *(LAS f32x4*)(vec + 1 * 2048 + sn * 64), k4n = *(LAS f32x4*)(vec + 2 * 2048 + sn * 64),
;                                     a4n = *(LAS f32x4*)(vec + 3 * 2048 + sn * 64), b4n = *(LAS f32x4*)(vec + 4 * 2048 + sn * 64);
;                         const float vn = Bf[10240 + sn * 16 + rl], cnn = Bf[18944 + sn];
;                         const f32x2 aL = {a4[0], a4[1]}, aH = {a4[2], a4[3]}, wL = {w4[0], w4[1]}, wH = {w4[2], w4[3]}, kL = {k4[0], k4[1]}, kH = {k4[2], k4[3]},
;                                     bL = {b4[0], b4[1]}, bH = {b4[2], b4[3]}, rL = {r4[0], r4[1]}, rH = {r4[2], r4[3]};
;                         const f32x2 uL = Sa * wL + kL * v, uH = Sb * wH + kH * v;
;                         const f32x2 dz = uL * aL + uH * aH;
;                         const float z = row16_sum(dz[0] + dz[1]);
;                         Sa = bL * sa + uL; Sb = bH * sa + uH;
;                         const f32x2 dr = Sa * rL + Sb * rH;
;                         yv[u] = dr[0] + dr[1];
;                         sa = z + cn * sa;
;                         r4 = r4n; w4 = w4n; k4 = k4n; a4 = a4n; b4 = b4n; v = vn; cn = cnn;
;                     }
; #pragma unroll
;                     for (int u = 0; u < 8; ++u) Bf[10752 + ((s0 + u) * 16 + rl) * 16 + jg] = yv[u];
	ds_read_b128 v[16:19], v0 offset:18944
	ds_read_b128 v[24:27], v0 offset:27136
	ds_read_b128 v[44:47], v0 offset:35072
	ds_read_b128 v[40:43], v0 offset:2304
	ds_read2_b32 v[98:99], v97 offset0:160 offset1:176
	v_pk_fma_f32 v[108:109], v[52:53], v[112:113], v[20:21] op_sel:[0,0,0] op_sel_hi:[1,0,1]
	v_pk_fma_f32 v[110:111], v[54:55], v[112:113], v[22:23] op_sel:[0,0,0] op_sel_hi:[1,0,1]
	ds_read_b128 v[20:23], v0 offset:10752
	v_add_f32_dpp v113, v113, v113 quad_perm:[1,0,3,2] row_mask:0xf bank_mask:0xf bound_ctrl:1
	v_pk_mul_f32 v[28:29], v[28:29], v[56:57] op_sel_hi:[1,0]
	v_pk_mul_f32 v[30:31], v[30:31], v[56:57] op_sel_hi:[1,0]
	v_pk_fma_f32 v[32:33], v[108:109], v[32:33], v[28:29]
	v_add_f32_dpp v113, v113, v113 quad_perm:[2,3,0,1] row_mask:0xf bank_mask:0xf bound_ctrl:1
	v_pk_fma_f32 v[34:35], v[110:111], v[34:35], v[30:31]
	v_pk_mul_f32 v[36:37], v[36:37], v[32:33]
	v_add_f32_dpp v113, v113, v113 row_half_mirror row_mask:0xf bank_mask:0xf bound_ctrl:1
	v_pk_mul_f32 v[48:49], v[48:49], v[108:109]
	v_pk_fma_f32 v[36:37], v[38:39], v[34:35], v[36:37]
	v_add_f32_dpp v113, v113, v113 row_mirror row_mask:0xf bank_mask:0xf bound_ctrl:1
	v_pk_fma_f32 v[48:49], v[50:51], v[110:111], v[48:49]
	v_fmac_f32_e32 v113, v161, v112
	v_add_f32_e32 v3, v48, v49
	v_add_f32_e32 v112, v36, v37
	ds_write2st64_b32 v158, v2, v3 offset0:24 offset1:28
	s_waitcnt lgkmcnt(7)
	ds_read_b128 v[28:31], v0 offset:19200
	ds_read_b128 v[36:39], v0 offset:27392
	ds_read_b128 v[52:55], v0 offset:35328
	ds_read_b128 v[48:51], v0 offset:2560
	ds_read2_b32 v[160:161], v157 offset0:10 offset1:11
	v_pk_fma_f32 v[108:109], v[104:105], v[112:113], v[32:33] op_sel:[0,1,0] op_sel_hi:[1,1,1]
	v_pk_fma_f32 v[110:111], v[106:107], v[112:113], v[34:35] op_sel:[0,1,0] op_sel_hi:[1,1,1]
	ds_read_b128 v[32:35], v0 offset:11008
	v_add_f32_dpp v112, v112, v112 quad_perm:[1,0,3,2] row_mask:0xf bank_mask:0xf bound_ctrl:1
	v_pk_mul_f32 v[4:5], v[4:5], v[56:57] op_sel:[0,1] op_sel_hi:[1,1]
	v_pk_mul_f32 v[6:7], v[6:7], v[56:57] op_sel:[0,1] op_sel_hi:[1,1]
	v_pk_fma_f32 v[8:9], v[108:109], v[8:9], v[4:5]
	v_add_f32_dpp v112, v112, v112 quad_perm:[2,3,0,1] row_mask:0xf bank_mask:0xf bound_ctrl:1
	v_pk_fma_f32 v[10:11], v[110:111], v[10:11], v[6:7]
	v_pk_mul_f32 v[12:13], v[12:13], v[8:9]
	v_add_f32_dpp v112, v112, v112 row_half_mirror row_mask:0xf bank_mask:0xf bound_ctrl:1
	v_pk_mul_f32 v[100:101], v[100:101], v[108:109]
	v_pk_fma_f32 v[12:13], v[14:15], v[10:11], v[12:13]
	v_add_f32_dpp v112, v112, v112 row_mirror row_mask:0xf bank_mask:0xf bound_ctrl:1
	v_pk_fma_f32 v[100:101], v[102:103], v[110:111], v[100:101]
	v_fmac_f32_e32 v112, v154, v113
	v_add_f32_e32 v2, v100, v101
	v_add_f32_e32 v113, v12, v13
	s_waitcnt lgkmcnt(7)
	ds_read_b128 v[4:7], v0 offset:19456
	ds_read_b128 v[12:15], v0 offset:27648
	ds_read_b128 v[104:107], v0 offset:35584
	ds_read_b128 v[100:103], v0 offset:2816
	ds_read2_b32 v[56:57], v97 offset0:192 offset1:208
	v_pk_fma_f32 v[108:109], v[44:45], v[112:113], v[8:9] op_sel:[0,0,0] op_sel_hi:[1,0,1]
	v_pk_fma_f32 v[110:111], v[46:47], v[112:113], v[10:11] op_sel:[0,0,0] op_sel_hi:[1,0,1]
	ds_read_b128 v[8:11], v0 offset:11264
	v_add_f32_dpp v113, v113, v113 quad_perm:[1,0,3,2] row_mask:0xf bank_mask:0xf bound_ctrl:1
	v_pk_mul_f32 v[16:17], v[16:17], v[98:99] op_sel_hi:[1,0]
	v_pk_mul_f32 v[18:19], v[18:19], v[98:99] op_sel_hi:[1,0]
	v_pk_fma_f32 v[20:21], v[108:109], v[20:21], v[16:17]
	v_add_f32_dpp v113, v113, v113 quad_perm:[2,3,0,1] row_mask:0xf bank_mask:0xf bound_ctrl:1
	v_pk_fma_f32 v[22:23], v[110:111], v[22:23], v[18:19]
	v_pk_mul_f32 v[24:25], v[24:25], v[20:21]
	v_add_f32_dpp v113, v113, v113 row_half_mirror row_mask:0xf bank_mask:0xf bound_ctrl:1
	v_pk_mul_f32 v[40:41], v[40:41], v[108:109]
	v_pk_fma_f32 v[24:25], v[26:27], v[22:23], v[24:25]
	v_add_f32_dpp v113, v113, v113 row_mirror row_mask:0xf bank_mask:0xf bound_ctrl:1
	v_pk_fma_f32 v[40:41], v[42:43], v[110:111], v[40:41]
	v_fmac_f32_e32 v113, v155, v112
	v_add_f32_e32 v3, v40, v41
	v_add_f32_e32 v112, v24, v25
	ds_write2st64_b32 v158, v2, v3 offset0:32 offset1:36
	s_waitcnt lgkmcnt(7)
	ds_read_b128 v[16:19], v0 offset:19712
	ds_read_b128 v[24:27], v0 offset:27904
	ds_read_b128 v[44:47], v0 offset:35840
	ds_read_b128 v[40:43], v0 offset:3072
	ds_read2_b32 v[154:155], v157 offset0:12 offset1:13
	v_pk_fma_f32 v[108:109], v[52:53], v[112:113], v[20:21] op_sel:[0,1,0] op_sel_hi:[1,1,1]
	v_pk_fma_f32 v[110:111], v[54:55], v[112:113], v[22:23] op_sel:[0,1,0] op_sel_hi:[1,1,1]
	ds_read_b128 v[20:23], v0 offset:11520
	v_add_f32_dpp v112, v112, v112 quad_perm:[1,0,3,2] row_mask:0xf bank_mask:0xf bound_ctrl:1
	v_pk_mul_f32 v[28:29], v[28:29], v[98:99] op_sel:[0,1] op_sel_hi:[1,1]
	v_pk_mul_f32 v[30:31], v[30:31], v[98:99] op_sel:[0,1] op_sel_hi:[1,1]
	v_pk_fma_f32 v[32:33], v[108:109], v[32:33], v[28:29]
	v_add_f32_dpp v112, v112, v112 quad_perm:[2,3,0,1] row_mask:0xf bank_mask:0xf bound_ctrl:1
	v_pk_fma_f32 v[34:35], v[110:111], v[34:35], v[30:31]
	v_pk_mul_f32 v[36:37], v[36:37], v[32:33]
	v_add_f32_dpp v112, v112, v112 row_half_mirror row_mask:0xf bank_mask:0xf bound_ctrl:1
	v_pk_mul_f32 v[48:49], v[48:49], v[108:109]
	v_pk_fma_f32 v[36:37], v[38:39], v[34:35], v[36:37]
	v_add_f32_dpp v112, v112, v112 row_mirror row_mask:0xf bank_mask:0xf bound_ctrl:1
	v_pk_fma_f32 v[48:49], v[50:51], v[110:111], v[48:49]
	v_fmac_f32_e32 v112, v160, v113
	v_add_f32_e32 v2, v48, v49
	v_add_f32_e32 v113, v36, v37
	s_waitcnt lgkmcnt(7)
; #define LAS __attribute__((address_space(3)))
; __device__ __forceinline__ float row16_sum(float x) { x += dpp_f<0xB1>(x); x += dpp_f<0x4E>(x); x += dpp_f<0x141>(x); x += dpp_f<0x140>(x); return x; }
; __device__ __forceinline__ void scan_phase(LAS unsigned char* lds, const h16* C1, const h16* DEC, const h16* AA, const h16* BB, float* Y, ...
;     ...
;                 for (int s0 = 0; s0 < CH; s0 += 8) {
;                     float yv[8];
; #pragma unroll
;                     for (int u = 0; u < 8; ++u) {
;                         const int s = s0 + u, sn = (s + 1 < CH) ? s + 1 : CH - 1;
;                         const f32x4 r4n = *(LAS f32x4*)(vec + 0 * 2048 + sn * 64), w4n = *(LAS f32x4*)(vec + 1 * 2048 + sn * 64), k4n = *(LAS f32x4*)(vec + 2 * 2048 + sn * 64),
;                                     a4n = *(LAS f32x4*)(vec + 3 * 2048 + sn * 64), b4n = *(LAS f32x4*)(vec + 4 * 2048 + sn * 64);
;                         const float vn = Bf[10240 + sn * 16 + rl], cnn = Bf[18944 + sn];
;                         const f32x2 aL = {a4[0], a4[1]}, aH = {a4[2], a4[3]}, wL = {w4[0], w4[1]}, wH = {w4[2], w4[3]}, kL = {k4[0], k4[1]}, kH = {k4[2], k4[3]},
;                                     bL = {b4[0], b4[1]}, bH = {b4[2], b4[3]}, rL = {r4[0], r4[1]}, rH = {r4[2], r4[3]};
;                         const f32x2 uL = Sa * wL + kL * v, uH = Sb * wH + kH * v;
;                         const f32x2 dz = uL * aL + uH * aH;
;                         const float z = row16_sum(dz[0] + dz[1]);
;                         Sa = bL * sa + uL; Sb = bH * sa + uH;
;                         const f32x2 dr = Sa * rL + Sb * rH;
;                         yv[u] = dr[0] + dr[1];
;                         sa = z + cn * sa;
;                         r4 = r4n; w4 = w4n; k4 = k4n; a4 = a4n; b4 = b4n; v = vn; cn = cnn;
;                     }
; #pragma unroll
;                     for (int u = 0; u < 8; ++u) Bf[10752 + ((s0 + u) * 16 + rl) * 16 + jg] = yv[u];
	ds_read_b128 v[28:31], v0 offset:19968
	ds_read_b128 v[36:39], v0 offset:28160
	ds_read_b128 v[52:55], v0 offset:36096
	ds_read_b128 v[48:51], v0 offset:3328
	ds_read2_b32 v[98:99], v97 offset0:224 offset1:240
	v_pk_fma_f32 v[108:109], v[104:105], v[112:113], v[32:33] op_sel:[0,0,0] op_sel_hi:[1,0,1]
	v_pk_fma_f32 v[110:111], v[106:107], v[112:113], v[34:35] op_sel:[0,0,0] op_sel_hi:[1,0,1]
	ds_read_b128 v[32:35], v0 offset:11776
	v_add_f32_dpp v113, v113, v113 quad_perm:[1,0,3,2] row_mask:0xf bank_mask:0xf bound_ctrl:1
	v_pk_mul_f32 v[4:5], v[4:5], v[56:57] op_sel_hi:[1,0]
	v_pk_mul_f32 v[6:7], v[6:7], v[56:57] op_sel_hi:[1,0]
	v_pk_fma_f32 v[8:9], v[108:109], v[8:9], v[4:5]
	v_add_f32_dpp v113, v113, v113 quad_perm:[2,3,0,1] row_mask:0xf bank_mask:0xf bound_ctrl:1
	v_pk_fma_f32 v[10:11], v[110:111], v[10:11], v[6:7]
	v_pk_mul_f32 v[12:13], v[12:13], v[8:9]
	v_add_f32_dpp v113, v113, v113 row_half_mirror row_mask:0xf bank_mask:0xf bound_ctrl:1
	v_pk_mul_f32 v[100:101], v[100:101], v[108:109]
	v_pk_fma_f32 v[12:13], v[14:15], v[10:11], v[12:13]
	v_add_f32_dpp v113, v113, v113 row_mirror row_mask:0xf bank_mask:0xf bound_ctrl:1
	v_pk_fma_f32 v[100:101], v[102:103], v[110:111], v[100:101]
	v_fmac_f32_e32 v113, v161, v112
	v_add_f32_e32 v3, v100, v101
	v_add_f32_e32 v112, v12, v13
	ds_write2st64_b32 v158, v2, v3 offset0:40 offset1:44
	s_waitcnt lgkmcnt(7)
	ds_read_b128 v[4:7], v0 offset:20224
	ds_read_b128 v[12:15], v0 offset:28416
	ds_read_b128 v[104:107], v0 offset:36352
	ds_read_b128 v[100:103], v0 offset:3584
	ds_read2_b32 v[160:161], v157 offset0:14 offset1:15
	v_pk_fma_f32 v[108:109], v[44:45], v[112:113], v[8:9] op_sel:[0,1,0] op_sel_hi:[1,1,1]
	v_pk_fma_f32 v[110:111], v[46:47], v[112:113], v[10:11] op_sel:[0,1,0] op_sel_hi:[1,1,1]
	ds_read_b128 v[8:11], v0 offset:12032
	v_add_f32_dpp v112, v112, v112 quad_perm:[1,0,3,2] row_mask:0xf bank_mask:0xf bound_ctrl:1
	v_pk_mul_f32 v[16:17], v[16:17], v[56:57] op_sel:[0,1] op_sel_hi:[1,1]
	v_pk_mul_f32 v[18:19], v[18:19], v[56:57] op_sel:[0,1] op_sel_hi:[1,1]
	v_pk_fma_f32 v[20:21], v[108:109], v[20:21], v[16:17]
	v_add_f32_dpp v112, v112, v112 quad_perm:[2,3,0,1] row_mask:0xf bank_mask:0xf bound_ctrl:1
	v_pk_fma_f32 v[22:23], v[110:111], v[22:23], v[18:19]
	v_pk_mul_f32 v[24:25], v[24:25], v[20:21]
	v_add_f32_dpp v112, v112, v112 row_half_mirror row_mask:0xf bank_mask:0xf bound_ctrl:1
	v_pk_mul_f32 v[40:41], v[40:41], v[108:109]
	v_pk_fma_f32 v[24:25], v[26:27], v[22:23], v[24:25]
	v_add_f32_dpp v112, v112, v112 row_mirror row_mask:0xf bank_mask:0xf bound_ctrl:1
	v_pk_fma_f32 v[40:41], v[42:43], v[110:111], v[40:41]
	v_fmac_f32_e32 v112, v154, v113
	v_add_f32_e32 v2, v40, v41
	v_add_f32_e32 v113, v24, v25
	s_waitcnt lgkmcnt(7)
	ds_read_b128 v[16:19], v0 offset:20480
	ds_read_b128 v[24:27], v0 offset:28672
	ds_read_b128 v[44:47], v0 offset:36608
	ds_read_b128 v[40:43], v0 offset:3840
	ds_read2_b32 v[56:57], v156 offset0:0 offset1:16
	v_pk_fma_f32 v[108:109], v[52:53], v[112:113], v[20:21] op_sel:[0,0,0] op_sel_hi:[1,0,1]
	v_pk_fma_f32 v[110:111], v[54:55], v[112:113], v[22:23] op_sel:[0,0,0] op_sel_hi:[1,0,1]
	ds_read_b128 v[20:23], v0 offset:12288
	v_add_f32_dpp v113, v113, v113 quad_perm:[1,0,3,2] row_mask:0xf bank_mask:0xf bound_ctrl:1
	v_pk_mul_f32 v[28:29], v[28:29], v[98:99] op_sel_hi:[1,0]
	v_pk_mul_f32 v[30:31], v[30:31], v[98:99] op_sel_hi:[1,0]
	v_pk_fma_f32 v[32:33], v[108:109], v[32:33], v[28:29]
	v_add_f32_dpp v113, v113, v113 quad_perm:[2,3,0,1] row_mask:0xf bank_mask:0xf bound_ctrl:1
	v_pk_fma_f32 v[34:35], v[110:111], v[34:35], v[30:31]
	v_pk_mul_f32 v[36:37], v[36:37], v[32:33]
	v_add_f32_dpp v113, v113, v113 row_half_mirror row_mask:0xf bank_mask:0xf bound_ctrl:1
	v_pk_mul_f32 v[48:49], v[48:49], v[108:109]
	v_pk_fma_f32 v[36:37], v[38:39], v[34:35], v[36:37]
	v_add_f32_dpp v113, v113, v113 row_mirror row_mask:0xf bank_mask:0xf bound_ctrl:1
	v_pk_fma_f32 v[48:49], v[50:51], v[110:111], v[48:49]
	v_fmac_f32_e32 v113, v155, v112
	v_add_f32_e32 v3, v48, v49
	v_add_f32_e32 v112, v36, v37
	ds_write2st64_b32 v158, v2, v3 offset0:48 offset1:52
	s_waitcnt lgkmcnt(7)
	ds_read_b128 v[28:31], v0 offset:20736
	ds_read_b128 v[36:39], v0 offset:28928
	ds_read_b128 v[52:55], v0 offset:36864
	ds_read_b128 v[48:51], v0 offset:4096
	ds_read2_b32 v[154:155], v157 offset0:16 offset1:17
	v_pk_fma_f32 v[108:109], v[104:105], v[112:113], v[32:33] op_sel:[0,1,0] op_sel_hi:[1,1,1]
	v_pk_fma_f32 v[110:111], v[106:107], v[112:113], v[34:35] op_sel:[0,1,0] op_sel_hi:[1,1,1]
	ds_read_b128 v[32:35], v0 offset:12544
	v_add_f32_dpp v112, v112, v112 quad_perm:[1,0,3,2] row_mask:0xf bank_mask:0xf bound_ctrl:1
	v_pk_mul_f32 v[4:5], v[4:5], v[98:99] op_sel:[0,1] op_sel_hi:[1,1]
	v_pk_mul_f32 v[6:7], v[6:7], v[98:99] op_sel:[0,1] op_sel_hi:[1,1]
	v_pk_fma_f32 v[8:9], v[108:109], v[8:9], v[4:5]
	v_add_f32_dpp v112, v112, v112 quad_perm:[2,3,0,1] row_mask:0xf bank_mask:0xf bound_ctrl:1
	v_pk_fma_f32 v[10:11], v[110:111], v[10:11], v[6:7]
	v_pk_mul_f32 v[12:13], v[12:13], v[8:9]
	v_add_f32_dpp v112, v112, v112 row_half_mirror row_mask:0xf bank_mask:0xf bound_ctrl:1
	v_pk_mul_f32 v[100:101], v[100:101], v[108:109]
	v_pk_fma_f32 v[12:13], v[14:15], v[10:11], v[12:13]
	v_add_f32_dpp v112, v112, v112 row_mirror row_mask:0xf bank_mask:0xf bound_ctrl:1
	v_pk_fma_f32 v[100:101], v[102:103], v[110:111], v[100:101]
	v_fmac_f32_e32 v112, v160, v113
	v_add_f32_e32 v2, v100, v101
	v_add_f32_e32 v113, v12, v13
	s_waitcnt lgkmcnt(7)
; #define LAS __attribute__((address_space(3)))
; __device__ __forceinline__ float row16_sum(float x) { x += dpp_f<0xB1>(x); x += dpp_f<0x4E>(x); x += dpp_f<0x141>(x); x += dpp_f<0x140>(x); return x; }
; __device__ __forceinline__ void scan_phase(LAS unsigned char* lds, const h16* C1, const h16* DEC, const h16* AA, const h16* BB, float* Y, ...
;     ...
;                 for (int s0 = 0; s0 < CH; s0 += 8) {
;                     float yv[8];
; #pragma unroll
;                     for (int u = 0; u < 8; ++u) {
;                         const int s = s0 + u, sn = (s + 1 < CH) ? s + 1 : CH - 1;
;                         const f32x4 r4n = *(LAS f32x4*)(vec + 0 * 2048 + sn * 64), w4n = *(LAS f32x4*)(vec + 1 * 2048 + sn * 64), k4n = *(LAS f32x4*)(vec + 2 * 2048 + sn * 64),
;                                     a4n = *(LAS f32x4*)(vec + 3 * 2048 + sn * 64), b4n = *(LAS f32x4*)(vec + 4 * 2048 + sn * 64);
;                         const float vn = Bf[10240 + sn * 16 + rl], cnn = Bf[18944 + sn];
;                         const f32x2 aL = {a4[0], a4[1]}, aH = {a4[2], a4[3]}, wL = {w4[0], w4[1]}, wH = {w4[2], w4[3]}, kL = {k4[0], k4[1]}, kH = {k4[2], k4[3]},
;                                     bL = {b4[0], b4[1]}, bH = {b4[2], b4[3]}, rL = {r4[0], r4[1]}, rH = {r4[2], r4[3]};
;                         const f32x2 uL = Sa * wL + kL * v, uH = Sb * wH + kH * v;
;                         const f32x2 dz = uL * aL + uH * aH;
;                         const float z = row16_sum(dz[0] + dz[1]);
;                         Sa = bL * sa + uL; Sb = bH * sa + uH;
;                         const f32x2 dr = Sa * rL + Sb * rH;
;                         yv[u] = dr[0] + dr[1];
;                         sa = z + cn * sa;
;                         r4 = r4n; w4 = w4n; k4 = k4n; a4 = a4n; b4 = b4n; v = vn; cn = cnn;
;                     }
; #pragma unroll
;                     for (int u = 0; u < 8; ++u) Bf[10752 + ((s0 + u) * 16 + rl) * 16 + jg] = yv[u];
	ds_read_b128 v[4:7], v0 offset:20992
	ds_read_b128 v[12:15], v0 offset:29184
	ds_read_b128 v[104:107], v0 offset:37120
	ds_read_b128 v[100:103], v0 offset:4352
	ds_read2_b32 v[98:99], v156 offset0:32 offset1:48
	v_pk_fma_f32 v[108:109], v[44:45], v[112:113], v[8:9] op_sel:[0,0,0] op_sel_hi:[1,0,1]
	v_pk_fma_f32 v[110:111], v[46:47], v[112:113], v[10:11] op_sel:[0,0,0] op_sel_hi:[1,0,1]
	ds_read_b128 v[8:11], v0 offset:12800
	v_add_f32_dpp v113, v113, v113 quad_perm:[1,0,3,2] row_mask:0xf bank_mask:0xf bound_ctrl:1
	v_pk_mul_f32 v[16:17], v[16:17], v[56:57] op_sel_hi:[1,0]
	v_pk_mul_f32 v[18:19], v[18:19], v[56:57] op_sel_hi:[1,0]
	v_pk_fma_f32 v[20:21], v[108:109], v[20:21], v[16:17]
	v_add_f32_dpp v113, v113, v113 quad_perm:[2,3,0,1] row_mask:0xf bank_mask:0xf bound_ctrl:1
	v_pk_fma_f32 v[22:23], v[110:111], v[22:23], v[18:19]
	v_pk_mul_f32 v[24:25], v[24:25], v[20:21]
	v_add_f32_dpp v113, v113, v113 row_half_mirror row_mask:0xf bank_mask:0xf bound_ctrl:1
	v_pk_mul_f32 v[40:41], v[40:41], v[108:109]
	v_pk_fma_f32 v[24:25], v[26:27], v[22:23], v[24:25]
	v_add_f32_dpp v113, v113, v113 row_mirror row_mask:0xf bank_mask:0xf bound_ctrl:1
	v_pk_fma_f32 v[40:41], v[42:43], v[110:111], v[40:41]
	v_fmac_f32_e32 v113, v161, v112
	v_add_f32_e32 v3, v40, v41
	v_add_f32_e32 v112, v24, v25
	ds_write2st64_b32 v158, v2, v3 offset0:56 offset1:60
	s_waitcnt lgkmcnt(7)
	ds_read_b128 v[16:19], v0 offset:21248
	ds_read_b128 v[24:27], v0 offset:29440
	ds_read_b128 v[44:47], v0 offset:37376
	ds_read_b128 v[40:43], v0 offset:4608
	ds_read2_b32 v[160:161], v157 offset0:18 offset1:19
	v_pk_fma_f32 v[108:109], v[52:53], v[112:113], v[20:21] op_sel:[0,1,0] op_sel_hi:[1,1,1]
	v_pk_fma_f32 v[110:111], v[54:55], v[112:113], v[22:23] op_sel:[0,1,0] op_sel_hi:[1,1,1]
	ds_read_b128 v[20:23], v0 offset:13056
	v_add_f32_dpp v112, v112, v112 quad_perm:[1,0,3,2] row_mask:0xf bank_mask:0xf bound_ctrl:1
	v_pk_mul_f32 v[28:29], v[28:29], v[56:57] op_sel:[0,1] op_sel_hi:[1,1]
	v_pk_mul_f32 v[30:31], v[30:31], v[56:57] op_sel:[0,1] op_sel_hi:[1,1]
	v_pk_fma_f32 v[32:33], v[108:109], v[32:33], v[28:29]
	v_add_f32_dpp v112, v112, v112 quad_perm:[2,3,0,1] row_mask:0xf bank_mask:0xf bound_ctrl:1
	v_pk_fma_f32 v[34:35], v[110:111], v[34:35], v[30:31]
	v_pk_mul_f32 v[36:37], v[36:37], v[32:33]
	v_add_f32_dpp v112, v112, v112 row_half_mirror row_mask:0xf bank_mask:0xf bound_ctrl:1
	v_pk_mul_f32 v[48:49], v[48:49], v[108:109]
	v_pk_fma_f32 v[36:37], v[38:39], v[34:35], v[36:37]
	v_add_f32_dpp v112, v112, v112 row_mirror row_mask:0xf bank_mask:0xf bound_ctrl:1
	v_pk_fma_f32 v[48:49], v[50:51], v[110:111], v[48:49]
	v_fmac_f32_e32 v112, v154, v113
	v_add_f32_e32 v2, v48, v49
	v_add_f32_e32 v113, v36, v37
	s_waitcnt lgkmcnt(7)
	ds_read_b128 v[28:31], v0 offset:21504
	ds_read_b128 v[36:39], v0 offset:29696
	ds_read_b128 v[52:55], v0 offset:37632
	ds_read_b128 v[48:51], v0 offset:4864
	ds_read2_b32 v[56:57], v156 offset0:64 offset1:80
	v_pk_fma_f32 v[108:109], v[104:105], v[112:113], v[32:33] op_sel:[0,0,0] op_sel_hi:[1,0,1]
	v_pk_fma_f32 v[110:111], v[106:107], v[112:113], v[34:35] op_sel:[0,0,0] op_sel_hi:[1,0,1]
	ds_read_b128 v[32:35], v0 offset:13312
	v_add_f32_dpp v113, v113, v113 quad_perm:[1,0,3,2] row_mask:0xf bank_mask:0xf bound_ctrl:1
	v_pk_mul_f32 v[4:5], v[4:5], v[98:99] op_sel_hi:[1,0]
	v_pk_mul_f32 v[6:7], v[6:7], v[98:99] op_sel_hi:[1,0]
	v_pk_fma_f32 v[8:9], v[108:109], v[8:9], v[4:5]
	v_add_f32_dpp v113, v113, v113 quad_perm:[2,3,0,1] row_mask:0xf bank_mask:0xf bound_ctrl:1
	v_pk_fma_f32 v[10:11], v[110:111], v[10:11], v[6:7]
	v_pk_mul_f32 v[12:13], v[12:13], v[8:9]
	v_add_f32_dpp v113, v113, v113 row_half_mirror row_mask:0xf bank_mask:0xf bound_ctrl:1
	v_pk_mul_f32 v[100:101], v[100:101], v[108:109]
	v_pk_fma_f32 v[12:13], v[14:15], v[10:11], v[12:13]
	v_add_f32_dpp v113, v113, v113 row_mirror row_mask:0xf bank_mask:0xf bound_ctrl:1
	v_pk_fma_f32 v[100:101], v[102:103], v[110:111], v[100:101]
	v_fmac_f32_e32 v113, v155, v112
	v_add_f32_e32 v3, v100, v101
	v_add_f32_e32 v112, v12, v13
	ds_write2st64_b32 v158, v2, v3 offset0:64 offset1:68
	s_waitcnt lgkmcnt(7)
	ds_read_b128 v[4:7], v0 offset:21760
	ds_read_b128 v[12:15], v0 offset:29952
	ds_read_b128 v[104:107], v0 offset:37888
	ds_read_b128 v[100:103], v0 offset:5120
	ds_read2_b32 v[154:155], v157 offset0:20 offset1:21
	v_pk_fma_f32 v[108:109], v[44:45], v[112:113], v[8:9] op_sel:[0,1,0] op_sel_hi:[1,1,1]
	v_pk_fma_f32 v[110:111], v[46:47], v[112:113], v[10:11] op_sel:[0,1,0] op_sel_hi:[1,1,1]
	ds_read_b128 v[8:11], v0 offset:13568
	v_add_f32_dpp v112, v112, v112 quad_perm:[1,0,3,2] row_mask:0xf bank_mask:0xf bound_ctrl:1
	v_pk_mul_f32 v[16:17], v[16:17], v[98:99] op_sel:[0,1] op_sel_hi:[1,1]
	v_pk_mul_f32 v[18:19], v[18:19], v[98:99] op_sel:[0,1] op_sel_hi:[1,1]
	v_pk_fma_f32 v[20:21], v[108:109], v[20:21], v[16:17]
	v_add_f32_dpp v112, v112, v112 quad_perm:[2,3,0,1] row_mask:0xf bank_mask:0xf bound_ctrl:1
	v_pk_fma_f32 v[22:23], v[110:111], v[22:23], v[18:19]
	v_pk_mul_f32 v[24:25], v[24:25], v[20:21]
	v_add_f32_dpp v112, v112, v112 row_half_mirror row_mask:0xf bank_mask:0xf bound_ctrl:1
	v_pk_mul_f32 v[40:41], v[40:41], v[108:109]
	v_pk_fma_f32 v[24:25], v[26:27], v[22:23], v[24:25]
	v_add_f32_dpp v112, v112, v112 row_mirror row_mask:0xf bank_mask:0xf bound_ctrl:1
	v_pk_fma_f32 v[40:41], v[42:43], v[110:111], v[40:41]
	v_fmac_f32_e32 v112, v160, v113
	v_add_f32_e32 v2, v40, v41
	v_add_f32_e32 v113, v24, v25
	s_waitcnt lgkmcnt(7)
; #define LAS __attribute__((address_space(3)))
; __device__ __forceinline__ float row16_sum(float x) { x += dpp_f<0xB1>(x); x += dpp_f<0x4E>(x); x += dpp_f<0x141>(x); x += dpp_f<0x140>(x); return x; }
; __device__ __forceinline__ void scan_phase(LAS unsigned char* lds, const h16* C1, const h16* DEC, const h16* AA, const h16* BB, float* Y, ...
;     ...
;                 for (int s0 = 0; s0 < CH; s0 += 8) {
;                     float yv[8];
; #pragma unroll
;                     for (int u = 0; u < 8; ++u) {
;                         const int s = s0 + u, sn = (s + 1 < CH) ? s + 1 : CH - 1;
;                         const f32x4 r4n = *(LAS f32x4*)(vec + 0 * 2048 + sn * 64), w4n = *(LAS f32x4*)(vec + 1 * 2048 + sn * 64), k4n = *(LAS f32x4*)(vec + 2 * 2048 + sn * 64),
;                                     a4n = *(LAS f32x4*)(vec + 3 * 2048 + sn * 64), b4n = *(LAS f32x4*)(vec + 4 * 2048 + sn * 64);
;                         const float vn = Bf[10240 + sn * 16 + rl], cnn = Bf[18944 + sn];
;                         const f32x2 aL = {a4[0], a4[1]}, aH = {a4[2], a4[3]}, wL = {w4[0], w4[1]}, wH = {w4[2], w4[3]}, kL = {k4[0], k4[1]}, kH = {k4[2], k4[3]},
;                                     bL = {b4[0], b4[1]}, bH = {b4[2], b4[3]}, rL = {r4[0], r4[1]}, rH = {r4[2], r4[3]};
;                         const f32x2 uL = Sa * wL + kL * v, uH = Sb * wH + kH * v;
;                         const f32x2 dz = uL * aL + uH * aH;
;                         const float z = row16_sum(dz[0] + dz[1]);
;                         Sa = bL * sa + uL; Sb = bH * sa + uH;
;                         const f32x2 dr = Sa * rL + Sb * rH;
;                         yv[u] = dr[0] + dr[1];
;                         sa = z + cn * sa;
;                         r4 = r4n; w4 = w4n; k4 = k4n; a4 = a4n; b4 = b4n; v = vn; cn = cnn;
;                     }
; #pragma unroll
;                     for (int u = 0; u < 8; ++u) Bf[10752 + ((s0 + u) * 16 + rl) * 16 + jg] = yv[u];
	ds_read_b128 v[16:19], v0 offset:22016
	ds_read_b128 v[24:27], v0 offset:30208
	ds_read_b128 v[44:47], v0 offset:38144
	ds_read_b128 v[40:43], v0 offset:5376
	ds_read2_b32 v[98:99], v156 offset0:96 offset1:112
	v_pk_fma_f32 v[108:109], v[52:53], v[112:113], v[20:21] op_sel:[0,0,0] op_sel_hi:[1,0,1]
	v_pk_fma_f32 v[110:111], v[54:55], v[112:113], v[22:23] op_sel:[0,0,0] op_sel_hi:[1,0,1]
	ds_read_b128 v[20:23], v0 offset:13824
	v_add_f32_dpp v113, v113, v113 quad_perm:[1,0,3,2] row_mask:0xf bank_mask:0xf bound_ctrl:1
	v_pk_mul_f32 v[28:29], v[28:29], v[56:57] op_sel_hi:[1,0]
	v_pk_mul_f32 v[30:31], v[30:31], v[56:57] op_sel_hi:[1,0]
	v_pk_fma_f32 v[32:33], v[108:109], v[32:33], v[28:29]
	v_add_f32_dpp v113, v113, v113 quad_perm:[2,3,0,1] row_mask:0xf bank_mask:0xf bound_ctrl:1
	v_pk_fma_f32 v[34:35], v[110:111], v[34:35], v[30:31]
	v_pk_mul_f32 v[36:37], v[36:37], v[32:33]
	v_add_f32_dpp v113, v113, v113 row_half_mirror row_mask:0xf bank_mask:0xf bound_ctrl:1
	v_pk_mul_f32 v[48:49], v[48:49], v[108:109]
	v_pk_fma_f32 v[36:37], v[38:39], v[34:35], v[36:37]
	v_add_f32_dpp v113, v113, v113 row_mirror row_mask:0xf bank_mask:0xf bound_ctrl:1
	v_pk_fma_f32 v[48:49], v[50:51], v[110:111], v[48:49]
	v_fmac_f32_e32 v113, v161, v112
	v_add_f32_e32 v3, v48, v49
	v_add_f32_e32 v112, v36, v37
	ds_write2st64_b32 v158, v2, v3 offset0:72 offset1:76
	s_waitcnt lgkmcnt(7)
	ds_read_b128 v[28:31], v0 offset:22272
	ds_read_b128 v[36:39], v0 offset:30464
	ds_read_b128 v[52:55], v0 offset:38400
	ds_read_b128 v[48:51], v0 offset:5632
	ds_read2_b32 v[160:161], v157 offset0:22 offset1:23
	v_pk_fma_f32 v[108:109], v[104:105], v[112:113], v[32:33] op_sel:[0,1,0] op_sel_hi:[1,1,1]
	v_pk_fma_f32 v[110:111], v[106:107], v[112:113], v[34:35] op_sel:[0,1,0] op_sel_hi:[1,1,1]
	ds_read_b128 v[32:35], v0 offset:14080
	v_add_f32_dpp v112, v112, v112 quad_perm:[1,0,3,2] row_mask:0xf bank_mask:0xf bound_ctrl:1
	v_pk_mul_f32 v[4:5], v[4:5], v[56:57] op_sel:[0,1] op_sel_hi:[1,1]
	v_pk_mul_f32 v[6:7], v[6:7], v[56:57] op_sel:[0,1] op_sel_hi:[1,1]
	v_pk_fma_f32 v[8:9], v[108:109], v[8:9], v[4:5]
	v_add_f32_dpp v112, v112, v112 quad_perm:[2,3,0,1] row_mask:0xf bank_mask:0xf bound_ctrl:1
	v_pk_fma_f32 v[10:11], v[110:111], v[10:11], v[6:7]
	v_pk_mul_f32 v[12:13], v[12:13], v[8:9]
	v_add_f32_dpp v112, v112, v112 row_half_mirror row_mask:0xf bank_mask:0xf bound_ctrl:1
	v_pk_mul_f32 v[100:101], v[100:101], v[108:109]
	v_pk_fma_f32 v[12:13], v[14:15], v[10:11], v[12:13]
	v_add_f32_dpp v112, v112, v112 row_mirror row_mask:0xf bank_mask:0xf bound_ctrl:1
	v_pk_fma_f32 v[100:101], v[102:103], v[110:111], v[100:101]
	v_fmac_f32_e32 v112, v154, v113
	v_add_f32_e32 v2, v100, v101
	v_add_f32_e32 v113, v12, v13
	s_waitcnt lgkmcnt(7)
	ds_read_b128 v[4:7], v0 offset:22528
	ds_read_b128 v[12:15], v0 offset:30720
	ds_read_b128 v[104:107], v0 offset:38656
	ds_read_b128 v[100:103], v0 offset:5888
	ds_read2_b32 v[56:57], v156 offset0:128 offset1:144
	v_pk_fma_f32 v[108:109], v[44:45], v[112:113], v[8:9] op_sel:[0,0,0] op_sel_hi:[1,0,1]
	v_pk_fma_f32 v[110:111], v[46:47], v[112:113], v[10:11] op_sel:[0,0,0] op_sel_hi:[1,0,1]
	ds_read_b128 v[8:11], v0 offset:14336
	v_add_f32_dpp v113, v113, v113 quad_perm:[1,0,3,2] row_mask:0xf bank_mask:0xf bound_ctrl:1
	v_pk_mul_f32 v[16:17], v[16:17], v[98:99] op_sel_hi:[1,0]
	v_pk_mul_f32 v[18:19], v[18:19], v[98:99] op_sel_hi:[1,0]
	v_pk_fma_f32 v[20:21], v[108:109], v[20:21], v[16:17]
	v_add_f32_dpp v113, v113, v113 quad_perm:[2,3,0,1] row_mask:0xf bank_mask:0xf bound_ctrl:1
	v_pk_fma_f32 v[22:23], v[110:111], v[22:23], v[18:19]
	v_pk_mul_f32 v[24:25], v[24:25], v[20:21]
	v_add_f32_dpp v113, v113, v113 row_half_mirror row_mask:0xf bank_mask:0xf bound_ctrl:1
	v_pk_mul_f32 v[40:41], v[40:41], v[108:109]
	v_pk_fma_f32 v[24:25], v[26:27], v[22:23], v[24:25]
	v_add_f32_dpp v113, v113, v113 row_mirror row_mask:0xf bank_mask:0xf bound_ctrl:1
	v_pk_fma_f32 v[40:41], v[42:43], v[110:111], v[40:41]
	v_fmac_f32_e32 v113, v155, v112
	v_add_f32_e32 v3, v40, v41
	v_add_f32_e32 v112, v24, v25
	ds_write2st64_b32 v158, v2, v3 offset0:80 offset1:84
	s_waitcnt lgkmcnt(7)
	ds_read_b128 v[16:19], v0 offset:22784
	ds_read_b128 v[24:27], v0 offset:30976
	ds_read_b128 v[44:47], v0 offset:38912
	ds_read_b128 v[40:43], v0 offset:6144
	ds_read2_b32 v[154:155], v157 offset0:24 offset1:25
	v_pk_fma_f32 v[108:109], v[52:53], v[112:113], v[20:21] op_sel:[0,1,0] op_sel_hi:[1,1,1]
	v_pk_fma_f32 v[110:111], v[54:55], v[112:113], v[22:23] op_sel:[0,1,0] op_sel_hi:[1,1,1]
	ds_read_b128 v[20:23], v0 offset:14592
	v_add_f32_dpp v112, v112, v112 quad_perm:[1,0,3,2] row_mask:0xf bank_mask:0xf bound_ctrl:1
	v_pk_mul_f32 v[28:29], v[28:29], v[98:99] op_sel:[0,1] op_sel_hi:[1,1]
	v_pk_mul_f32 v[30:31], v[30:31], v[98:99] op_sel:[0,1] op_sel_hi:[1,1]
	v_pk_fma_f32 v[32:33], v[108:109], v[32:33], v[28:29]
	v_add_f32_dpp v112, v112, v112 quad_perm:[2,3,0,1] row_mask:0xf bank_mask:0xf bound_ctrl:1
	v_pk_fma_f32 v[34:35], v[110:111], v[34:35], v[30:31]
	v_pk_mul_f32 v[36:37], v[36:37], v[32:33]
	v_add_f32_dpp v112, v112, v112 row_half_mirror row_mask:0xf bank_mask:0xf bound_ctrl:1
	v_pk_mul_f32 v[48:49], v[48:49], v[108:109]
	v_pk_fma_f32 v[36:37], v[38:39], v[34:35], v[36:37]
	v_add_f32_dpp v112, v112, v112 row_mirror row_mask:0xf bank_mask:0xf bound_ctrl:1
	v_pk_fma_f32 v[48:49], v[50:51], v[110:111], v[48:49]
	v_fmac_f32_e32 v112, v160, v113
	v_add_f32_e32 v2, v48, v49
	v_add_f32_e32 v113, v36, v37
	s_waitcnt lgkmcnt(7)
; #define LAS __attribute__((address_space(3)))
; __device__ __forceinline__ float row16_sum(float x) { x += dpp_f<0xB1>(x); x += dpp_f<0x4E>(x); x += dpp_f<0x141>(x); x += dpp_f<0x140>(x); return x; }
; __device__ __forceinline__ void scan_phase(LAS unsigned char* lds, const h16* C1, const h16* DEC, const h16* AA, const h16* BB, float* Y, ...
;     ...
;                 for (int s0 = 0; s0 < CH; s0 += 8) {
;                     float yv[8];
; #pragma unroll
;                     for (int u = 0; u < 8; ++u) {
;                         const int s = s0 + u, sn = (s + 1 < CH) ? s + 1 : CH - 1;
;                         const f32x4 r4n = *(LAS f32x4*)(vec + 0 * 2048 + sn * 64), w4n = *(LAS f32x4*)(vec + 1 * 2048 + sn * 64), k4n = *(LAS f32x4*)(vec + 2 * 2048 + sn * 64),
;                                     a4n = *(LAS f32x4*)(vec + 3 * 2048 + sn * 64), b4n = *(LAS f32x4*)(vec + 4 * 2048 + sn * 64);
;                         const float vn = Bf[10240 + sn * 16 + rl], cnn = Bf[18944 + sn];
;                         const f32x2 aL = {a4[0], a4[1]}, aH = {a4[2], a4[3]}, wL = {w4[0], w4[1]}, wH = {w4[2], w4[3]}, kL = {k4[0], k4[1]}, kH = {k4[2], k4[3]},
;                                     bL = {b4[0], b4[1]}, bH = {b4[2], b4[3]}, rL = {r4[0], r4[1]}, rH = {r4[2], r4[3]};
;                         const f32x2 uL = Sa * wL + kL * v, uH = Sb * wH + kH * v;
;                         const f32x2 dz = uL * aL + uH * aH;
;                         const float z = row16_sum(dz[0] + dz[1]);
;                         Sa = bL * sa + uL; Sb = bH * sa + uH;
;                         const f32x2 dr = Sa * rL + Sb * rH;
;                         yv[u] = dr[0] + dr[1];
;                         sa = z + cn * sa;
;                         r4 = r4n; w4 = w4n; k4 = k4n; a4 = a4n; b4 = b4n; v = vn; cn = cnn;
;                     }
; #pragma unroll
;                     for (int u = 0; u < 8; ++u) Bf[10752 + ((s0 + u) * 16 + rl) * 16 + jg] = yv[u];
	ds_read_b128 v[28:31], v0 offset:23040
	ds_read_b128 v[36:39], v0 offset:31232
	ds_read_b128 v[52:55], v0 offset:39168
	ds_read_b128 v[48:51], v0 offset:6400
	ds_read2_b32 v[98:99], v156 offset0:160 offset1:176
	v_pk_fma_f32 v[108:109], v[104:105], v[112:113], v[32:33] op_sel:[0,0,0] op_sel_hi:[1,0,1]
	v_pk_fma_f32 v[110:111], v[106:107], v[112:113], v[34:35] op_sel:[0,0,0] op_sel_hi:[1,0,1]
	ds_read_b128 v[32:35], v0 offset:14848
	v_add_f32_dpp v113, v113, v113 quad_perm:[1,0,3,2] row_mask:0xf bank_mask:0xf bound_ctrl:1
	v_pk_mul_f32 v[4:5], v[4:5], v[56:57] op_sel_hi:[1,0]
	v_pk_mul_f32 v[6:7], v[6:7], v[56:57] op_sel_hi:[1,0]
	v_pk_fma_f32 v[8:9], v[108:109], v[8:9], v[4:5]
	v_add_f32_dpp v113, v113, v113 quad_perm:[2,3,0,1] row_mask:0xf bank_mask:0xf bound_ctrl:1
	v_pk_fma_f32 v[10:11], v[110:111], v[10:11], v[6:7]
	v_pk_mul_f32 v[12:13], v[12:13], v[8:9]
	v_add_f32_dpp v113, v113, v113 row_half_mirror row_mask:0xf bank_mask:0xf bound_ctrl:1
	v_pk_mul_f32 v[100:101], v[100:101], v[108:109]
	v_pk_fma_f32 v[12:13], v[14:15], v[10:11], v[12:13]
	v_add_f32_dpp v113, v113, v113 row_mirror row_mask:0xf bank_mask:0xf bound_ctrl:1
	v_pk_fma_f32 v[100:101], v[102:103], v[110:111], v[100:101]
	v_fmac_f32_e32 v113, v161, v112
	v_add_f32_e32 v3, v100, v101
	v_add_f32_e32 v112, v12, v13
	ds_write2st64_b32 v158, v2, v3 offset0:88 offset1:92
	s_waitcnt lgkmcnt(7)
	ds_read_b128 v[4:7], v0 offset:23296
	ds_read_b128 v[12:15], v0 offset:31488
	ds_read_b128 v[104:107], v0 offset:39424
	ds_read_b128 v[100:103], v0 offset:6656
	ds_read2_b32 v[160:161], v157 offset0:26 offset1:27
	v_pk_fma_f32 v[108:109], v[44:45], v[112:113], v[8:9] op_sel:[0,1,0] op_sel_hi:[1,1,1]
	v_pk_fma_f32 v[110:111], v[46:47], v[112:113], v[10:11] op_sel:[0,1,0] op_sel_hi:[1,1,1]
	ds_read_b128 v[8:11], v0 offset:15104
	v_add_f32_dpp v112, v112, v112 quad_perm:[1,0,3,2] row_mask:0xf bank_mask:0xf bound_ctrl:1
	v_pk_mul_f32 v[16:17], v[16:17], v[56:57] op_sel:[0,1] op_sel_hi:[1,1]
	v_pk_mul_f32 v[18:19], v[18:19], v[56:57] op_sel:[0,1] op_sel_hi:[1,1]
	v_pk_fma_f32 v[20:21], v[108:109], v[20:21], v[16:17]
	v_add_f32_dpp v112, v112, v112 quad_perm:[2,3,0,1] row_mask:0xf bank_mask:0xf bound_ctrl:1
	v_pk_fma_f32 v[22:23], v[110:111], v[22:23], v[18:19]
	v_pk_mul_f32 v[24:25], v[24:25], v[20:21]
	v_add_f32_dpp v112, v112, v112 row_half_mirror row_mask:0xf bank_mask:0xf bound_ctrl:1
	v_pk_mul_f32 v[40:41], v[40:41], v[108:109]
	v_pk_fma_f32 v[24:25], v[26:27], v[22:23], v[24:25]
	v_add_f32_dpp v112, v112, v112 row_mirror row_mask:0xf bank_mask:0xf bound_ctrl:1
	v_pk_fma_f32 v[40:41], v[42:43], v[110:111], v[40:41]
	v_fmac_f32_e32 v112, v154, v113
	v_add_f32_e32 v2, v40, v41
	v_add_f32_e32 v113, v24, v25
	s_waitcnt lgkmcnt(7)
	ds_read_b128 v[16:19], v0 offset:23552
	ds_read_b128 v[24:27], v0 offset:31744
	ds_read_b128 v[44:47], v0 offset:39680
	ds_read_b128 v[40:43], v0 offset:6912
	ds_read2_b32 v[56:57], v156 offset0:192 offset1:208
	v_pk_fma_f32 v[108:109], v[52:53], v[112:113], v[20:21] op_sel:[0,0,0] op_sel_hi:[1,0,1]
	v_pk_fma_f32 v[110:111], v[54:55], v[112:113], v[22:23] op_sel:[0,0,0] op_sel_hi:[1,0,1]
	ds_read_b128 v[20:23], v0 offset:15360
	v_add_f32_dpp v113, v113, v113 quad_perm:[1,0,3,2] row_mask:0xf bank_mask:0xf bound_ctrl:1
	v_pk_mul_f32 v[28:29], v[28:29], v[98:99] op_sel_hi:[1,0]
	v_pk_mul_f32 v[30:31], v[30:31], v[98:99] op_sel_hi:[1,0]
	v_pk_fma_f32 v[32:33], v[108:109], v[32:33], v[28:29]
	v_add_f32_dpp v113, v113, v113 quad_perm:[2,3,0,1] row_mask:0xf bank_mask:0xf bound_ctrl:1
	v_pk_fma_f32 v[34:35], v[110:111], v[34:35], v[30:31]
	v_pk_mul_f32 v[36:37], v[36:37], v[32:33]
	v_add_f32_dpp v113, v113, v113 row_half_mirror row_mask:0xf bank_mask:0xf bound_ctrl:1
	v_pk_mul_f32 v[48:49], v[48:49], v[108:109]
	v_pk_fma_f32 v[36:37], v[38:39], v[34:35], v[36:37]
	v_add_f32_dpp v113, v113, v113 row_mirror row_mask:0xf bank_mask:0xf bound_ctrl:1
	v_pk_fma_f32 v[48:49], v[50:51], v[110:111], v[48:49]
	v_fmac_f32_e32 v113, v155, v112
	v_add_f32_e32 v3, v48, v49
	v_add_f32_e32 v112, v36, v37
	ds_write2st64_b32 v158, v2, v3 offset0:96 offset1:100
	s_waitcnt lgkmcnt(7)
	ds_read_b128 v[28:31], v0 offset:23808
	ds_read_b128 v[36:39], v0 offset:32000
	ds_read_b128 v[52:55], v0 offset:39936
	ds_read_b128 v[48:51], v0 offset:7168
	ds_read2_b32 v[154:155], v157 offset0:28 offset1:29
	v_pk_fma_f32 v[108:109], v[104:105], v[112:113], v[32:33] op_sel:[0,1,0] op_sel_hi:[1,1,1]
	v_pk_fma_f32 v[110:111], v[106:107], v[112:113], v[34:35] op_sel:[0,1,0] op_sel_hi:[1,1,1]
	ds_read_b128 v[32:35], v0 offset:15616
	v_add_f32_dpp v112, v112, v112 quad_perm:[1,0,3,2] row_mask:0xf bank_mask:0xf bound_ctrl:1
	v_pk_mul_f32 v[4:5], v[4:5], v[98:99] op_sel:[0,1] op_sel_hi:[1,1]
	v_pk_mul_f32 v[6:7], v[6:7], v[98:99] op_sel:[0,1] op_sel_hi:[1,1]
	v_pk_fma_f32 v[8:9], v[108:109], v[8:9], v[4:5]
	v_add_f32_dpp v112, v112, v112 quad_perm:[2,3,0,1] row_mask:0xf bank_mask:0xf bound_ctrl:1
	v_pk_fma_f32 v[10:11], v[110:111], v[10:11], v[6:7]
	v_pk_mul_f32 v[12:13], v[12:13], v[8:9]
	v_add_f32_dpp v112, v112, v112 row_half_mirror row_mask:0xf bank_mask:0xf bound_ctrl:1
	v_pk_mul_f32 v[100:101], v[100:101], v[108:109]
	v_pk_fma_f32 v[12:13], v[14:15], v[10:11], v[12:13]
	v_add_f32_dpp v112, v112, v112 row_mirror row_mask:0xf bank_mask:0xf bound_ctrl:1
	v_pk_fma_f32 v[100:101], v[102:103], v[110:111], v[100:101]
	v_fmac_f32_e32 v112, v160, v113
	v_add_f32_e32 v2, v100, v101
	v_add_f32_e32 v113, v12, v13
	s_waitcnt lgkmcnt(7)
; #define LAS __attribute__((address_space(3)))
; __device__ __forceinline__ float row16_sum(float x) { x += dpp_f<0xB1>(x); x += dpp_f<0x4E>(x); x += dpp_f<0x141>(x); x += dpp_f<0x140>(x); return x; }
; __device__ __forceinline__ void scan_phase(LAS unsigned char* lds, const h16* C1, const h16* DEC, const h16* AA, const h16* BB, float* Y, ...
;     ...
;                 for (int s0 = 0; s0 < CH; s0 += 8) {
;                     float yv[8];
; #pragma unroll
;                     for (int u = 0; u < 8; ++u) {
;                         const int s = s0 + u, sn = (s + 1 < CH) ? s + 1 : CH - 1;
;                         const f32x4 r4n = *(LAS f32x4*)(vec + 0 * 2048 + sn * 64), w4n = *(LAS f32x4*)(vec + 1 * 2048 + sn * 64), k4n = *(LAS f32x4*)(vec + 2 * 2048 + sn * 64),
;                                     a4n = *(LAS f32x4*)(vec + 3 * 2048 + sn * 64), b4n = *(LAS f32x4*)(vec + 4 * 2048 + sn * 64);
;                         const float vn = Bf[10240 + sn * 16 + rl], cnn = Bf[18944 + sn];
;                         const f32x2 aL = {a4[0], a4[1]}, aH = {a4[2], a4[3]}, wL = {w4[0], w4[1]}, wH = {w4[2], w4[3]}, kL = {k4[0], k4[1]}, kH = {k4[2], k4[3]},
;                                     bL = {b4[0], b4[1]}, bH = {b4[2], b4[3]}, rL = {r4[0], r4[1]}, rH = {r4[2], r4[3]};
;                         const f32x2 uL = Sa * wL + kL * v, uH = Sb * wH + kH * v;
;                         const f32x2 dz = uL * aL + uH * aH;
;                         const float z = row16_sum(dz[0] + dz[1]);
;                         Sa = bL * sa + uL; Sb = bH * sa + uH;
;                         const f32x2 dr = Sa * rL + Sb * rH;
;                         yv[u] = dr[0] + dr[1];
;                         sa = z + cn * sa;
;                         r4 = r4n; w4 = w4n; k4 = k4n; a4 = a4n; b4 = b4n; v = vn; cn = cnn;
;                     }
; #pragma unroll
;                     for (int u = 0; u < 8; ++u) Bf[10752 + ((s0 + u) * 16 + rl) * 16 + jg] = yv[u];
;                 }
;                 __syncthreads();
	ds_read_b128 v[4:7], v0 offset:24064
	ds_read_b128 v[12:15], v0 offset:32256
	ds_read_b128 v[104:107], v0 offset:40192
	ds_read_b128 v[100:103], v0 offset:7424
	ds_read2_b32 v[98:99], v156 offset0:224 offset1:240
	v_pk_fma_f32 v[108:109], v[44:45], v[112:113], v[8:9] op_sel:[0,0,0] op_sel_hi:[1,0,1]
	v_pk_fma_f32 v[110:111], v[46:47], v[112:113], v[10:11] op_sel:[0,0,0] op_sel_hi:[1,0,1]
	ds_read_b128 v[8:11], v0 offset:15872
	v_add_f32_dpp v113, v113, v113 quad_perm:[1,0,3,2] row_mask:0xf bank_mask:0xf bound_ctrl:1
	v_pk_mul_f32 v[16:17], v[16:17], v[56:57] op_sel_hi:[1,0]
	v_pk_mul_f32 v[18:19], v[18:19], v[56:57] op_sel_hi:[1,0]
	v_pk_fma_f32 v[20:21], v[108:109], v[20:21], v[16:17]
	v_add_f32_dpp v113, v113, v113 quad_perm:[2,3,0,1] row_mask:0xf bank_mask:0xf bound_ctrl:1
	v_pk_fma_f32 v[22:23], v[110:111], v[22:23], v[18:19]
	v_pk_mul_f32 v[24:25], v[24:25], v[20:21]
	v_add_f32_dpp v113, v113, v113 row_half_mirror row_mask:0xf bank_mask:0xf bound_ctrl:1
	v_pk_mul_f32 v[40:41], v[40:41], v[108:109]
	v_pk_fma_f32 v[24:25], v[26:27], v[22:23], v[24:25]
	v_add_f32_dpp v113, v113, v113 row_mirror row_mask:0xf bank_mask:0xf bound_ctrl:1
	v_pk_fma_f32 v[40:41], v[42:43], v[110:111], v[40:41]
	v_fmac_f32_e32 v113, v161, v112
	v_add_f32_e32 v3, v40, v41
	v_add_f32_e32 v112, v24, v25
	ds_write2st64_b32 v158, v2, v3 offset0:104 offset1:108
	s_waitcnt lgkmcnt(7)
	ds_read_b128 v[16:19], v0 offset:24320
	ds_read_b128 v[24:27], v0 offset:32512
	ds_read_b128 v[44:47], v0 offset:40448
	ds_read_b128 v[40:43], v0 offset:7680
	ds_read2_b32 v[160:161], v157 offset0:30 offset1:31
	v_pk_fma_f32 v[108:109], v[52:53], v[112:113], v[20:21] op_sel:[0,1,0] op_sel_hi:[1,1,1]
	v_pk_fma_f32 v[110:111], v[54:55], v[112:113], v[22:23] op_sel:[0,1,0] op_sel_hi:[1,1,1]
	ds_read_b128 v[20:23], v0 offset:16128
	v_add_f32_dpp v112, v112, v112 quad_perm:[1,0,3,2] row_mask:0xf bank_mask:0xf bound_ctrl:1
	v_pk_mul_f32 v[28:29], v[28:29], v[56:57] op_sel:[0,1] op_sel_hi:[1,1]
	v_pk_mul_f32 v[30:31], v[30:31], v[56:57] op_sel:[0,1] op_sel_hi:[1,1]
	v_pk_fma_f32 v[32:33], v[108:109], v[32:33], v[28:29]
	v_add_f32_dpp v112, v112, v112 quad_perm:[2,3,0,1] row_mask:0xf bank_mask:0xf bound_ctrl:1
	v_pk_fma_f32 v[34:35], v[110:111], v[34:35], v[30:31]
	v_pk_mul_f32 v[36:37], v[36:37], v[32:33]
	v_add_f32_dpp v112, v112, v112 row_half_mirror row_mask:0xf bank_mask:0xf bound_ctrl:1
	v_pk_mul_f32 v[48:49], v[48:49], v[108:109]
	v_pk_fma_f32 v[36:37], v[38:39], v[34:35], v[36:37]
	v_add_f32_dpp v112, v112, v112 row_mirror row_mask:0xf bank_mask:0xf bound_ctrl:1
	v_pk_fma_f32 v[48:49], v[50:51], v[110:111], v[48:49]
	v_fmac_f32_e32 v112, v154, v113
	v_add_f32_e32 v2, v48, v49
	v_add_f32_e32 v113, v36, v37
	s_waitcnt lgkmcnt(7)
	ds_read_b128 v[52:55], v0 offset:40704
	ds_read_b128 v[48:51], v0 offset:7936
	v_pk_fma_f32 v[108:109], v[104:105], v[112:113], v[32:33] op_sel:[0,0,0] op_sel_hi:[1,0,1]
	v_pk_fma_f32 v[110:111], v[106:107], v[112:113], v[34:35] op_sel:[0,0,0] op_sel_hi:[1,0,1]
	v_add_f32_dpp v113, v113, v113 quad_perm:[1,0,3,2] row_mask:0xf bank_mask:0xf bound_ctrl:1
	v_pk_mul_f32 v[4:5], v[4:5], v[98:99] op_sel_hi:[1,0]
	v_pk_mul_f32 v[6:7], v[6:7], v[98:99] op_sel_hi:[1,0]
	v_pk_fma_f32 v[8:9], v[108:109], v[8:9], v[4:5]
	v_add_f32_dpp v113, v113, v113 quad_perm:[2,3,0,1] row_mask:0xf bank_mask:0xf bound_ctrl:1
	v_pk_fma_f32 v[10:11], v[110:111], v[10:11], v[6:7]
	v_pk_mul_f32 v[12:13], v[12:13], v[8:9]
	v_add_f32_dpp v113, v113, v113 row_half_mirror row_mask:0xf bank_mask:0xf bound_ctrl:1
	v_pk_mul_f32 v[100:101], v[100:101], v[108:109]
	v_pk_fma_f32 v[12:13], v[14:15], v[10:11], v[12:13]
	v_add_f32_dpp v113, v113, v113 row_mirror row_mask:0xf bank_mask:0xf bound_ctrl:1
	v_pk_fma_f32 v[100:101], v[102:103], v[110:111], v[100:101]
	v_fmac_f32_e32 v113, v155, v112
	v_add_f32_e32 v3, v100, v101
	v_add_f32_e32 v112, v12, v13
	ds_write2st64_b32 v158, v2, v3 offset0:112 offset1:116
	s_waitcnt lgkmcnt(3)
	v_pk_fma_f32 v[108:109], v[44:45], v[112:113], v[8:9] op_sel:[0,1,0] op_sel_hi:[1,1,1]
	v_pk_fma_f32 v[110:111], v[46:47], v[112:113], v[10:11] op_sel:[0,1,0] op_sel_hi:[1,1,1]
	v_add_f32_dpp v112, v112, v112 quad_perm:[1,0,3,2] row_mask:0xf bank_mask:0xf bound_ctrl:1
	v_pk_mul_f32 v[16:17], v[16:17], v[98:99] op_sel:[0,1] op_sel_hi:[1,1]
	v_pk_mul_f32 v[18:19], v[18:19], v[98:99] op_sel:[0,1] op_sel_hi:[1,1]
	v_pk_fma_f32 v[20:21], v[108:109], v[20:21], v[16:17]
	v_add_f32_dpp v112, v112, v112 quad_perm:[2,3,0,1] row_mask:0xf bank_mask:0xf bound_ctrl:1
	v_pk_fma_f32 v[22:23], v[110:111], v[22:23], v[18:19]
	v_pk_mul_f32 v[24:25], v[24:25], v[20:21]
	v_add_f32_dpp v112, v112, v112 row_half_mirror row_mask:0xf bank_mask:0xf bound_ctrl:1
	v_pk_mul_f32 v[40:41], v[40:41], v[108:109]
	v_pk_fma_f32 v[24:25], v[26:27], v[22:23], v[24:25]
	v_add_f32_dpp v112, v112, v112 row_mirror row_mask:0xf bank_mask:0xf bound_ctrl:1
	v_pk_fma_f32 v[40:41], v[42:43], v[110:111], v[40:41]
	v_fmac_f32_e32 v112, v160, v113
	v_add_f32_e32 v2, v40, v41
	v_add_f32_e32 v113, v24, v25
	s_waitcnt lgkmcnt(1)
	v_pk_fma_f32 v[108:109], v[52:53], v[112:113], v[20:21] op_sel:[0,0,0] op_sel_hi:[1,0,1]
	v_pk_fma_f32 v[110:111], v[54:55], v[112:113], v[22:23] op_sel:[0,0,0] op_sel_hi:[1,0,1]
	v_add_f32_dpp v113, v113, v113 quad_perm:[1,0,3,2] row_mask:0xf bank_mask:0xf bound_ctrl:1
	s_nop 1
	v_add_f32_dpp v113, v113, v113 quad_perm:[2,3,0,1] row_mask:0xf bank_mask:0xf bound_ctrl:1
	s_nop 1
	v_add_f32_dpp v113, v113, v113 row_half_mirror row_mask:0xf bank_mask:0xf bound_ctrl:1
	v_pk_mul_f32 v[48:49], v[48:49], v[108:109]
	s_nop 0
	v_add_f32_dpp v113, v113, v113 row_mirror row_mask:0xf bank_mask:0xf bound_ctrl:1
	v_pk_fma_f32 v[48:49], v[50:51], v[110:111], v[48:49]
	v_fmac_f32_e32 v113, v161, v112
	v_add_f32_e32 v3, v48, v49
	ds_write2st64_b32 v158, v2, v3 offset0:120 offset1:124
	s_add_i32 s24, s24, 1
	s_cmpk_lg_i32 s24, 0x100
	s_waitcnt lgkmcnt(0)
	s_barrier
	s_cbranch_scc1 .Lscan_chunk

; #define LAS __attribute__((address_space(3)))
; __device__ __forceinline__ void scan_phase(LAS unsigned char* lds, const h16* C1, const h16* DEC, const h16* AA, const h16* BB, float* Y, ...
;     ...
;             auto gload = [&](int c) -> StReg {
;                 StReg R;
;                 const size_t row = row0 + (size_t)c * CH + s;
;                 R.r8 = *(const h16x8*)(C1 + row * LDC1 + h * 64 + e8 * 8);
;                 R.k8 = *(const h16x8*)(C1 + row * LDC1 + 2048 + h * 64 + e8 * 8);
;                 { const int tn = c * CH + s + 1; const size_t rown = row0 + (size_t)(tn < SEQ ? tn : SEQ - 1);
;                   R.a8 = *(const h16x8*)(AA + rown * DM + h * 64 + e8 * 8); }
;                 R.b8 = *(const h16x8*)(BB + row * DM + h * 64 + e8 * 8);
;                 R.d8 = *(const h16x8*)(DEC + row * DM + h * 64 + e8 * 8);
;                 R.v8 = (h16x8){};
;                 if (lt < 64) R.v8 = *(const h16x8*)(C1 + (row0 + (size_t)c * CH + (lt >> 1)) * LDC1 + 4096 + h * 64 + q * 16 + (lt & 1) * 8);
;                 return R;
;             };
;             auto lwrite = [&](const StReg& R, int bufi) {
;                 LAS float* Bf = L + bufi * BUF;
;                 LAS float* dst = Bf + s * 64 + e8 * 8;
;                 *(LAS f32x4*)(dst + 0 * 2048) = (f32x4){(float)R.r8[0], (float)R.r8[1], (float)R.r8[2], (float)R.r8[3]}; *(LAS f32x4*)(dst + 0 * 2048 + 4) = (f32x4){(float)R.r8[4], (float)R.r8[5], (float)R.r8[6], (float)R.r8[7]};
;                 *(LAS f32x4*)(dst + 1 * 2048) = (f32x4){__expf(-(float)R.d8[0]), __expf(-(float)R.d8[1]), __expf(-(float)R.d8[2]), __expf(-(float)R.d8[3])};
;                 *(LAS f32x4*)(dst + 1 * 2048 + 4) = (f32x4){__expf(-(float)R.d8[4]), __expf(-(float)R.d8[5]), __expf(-(float)R.d8[6]), __expf(-(float)R.d8[7])};
;                 *(LAS f32x4*)(dst + 2 * 2048) = (f32x4){(float)R.k8[0], (float)R.k8[1], (float)R.k8[2], (float)R.k8[3]}; *(LAS f32x4*)(dst + 2 * 2048 + 4) = (f32x4){(float)R.k8[4], (float)R.k8[5], (float)R.k8[6], (float)R.k8[7]};
;                 *(LAS f32x4*)(dst + 3 * 2048) = (f32x4){(float)R.a8[0], (float)R.a8[1], (float)R.a8[2], (float)R.a8[3]}; *(LAS f32x4*)(dst + 3 * 2048 + 4) = (f32x4){(float)R.a8[4], (float)R.a8[5], (float)R.a8[6], (float)R.a8[7]};
.LBB0_465:
	s_or_b64 exec, exec, s[26:27]
	s_lshl_b32 s20, s64, 1
	s_and_b32 s29, s20, 0xf80
	s_lshl_b32 s20, s64, 2
	s_and_b32 s35, s20, 0x1f00
	s_mul_i32 s20, s22, 0x7000000
	s_mul_hi_i32 s21, s22, 0x7000000
	s_or_b32 s20, s20, s29
	v_lshl_add_u64 v[10:11], s[20:21], 0, v[86:87]
	v_lshl_add_u64 v[108:109], s[20:21], 0, v[90:91]
	s_lshl_b64 s[20:21], s[22:23], 26
	s_or_b32 s20, s20, s35
	s_waitcnt lgkmcnt(0)
	s_barrier
	v_lshl_add_u64 v[104:105], v[98:99], 1, v[10:11]
	s_lshl_b64 s[26:27], s[22:23], 25
	v_lshl_add_u64 v[10:11], s[20:21], 0, v[92:93]
	v_lshlrev_b64 v[12:13], 2, v[98:99]
	s_or_b32 s26, s26, s29
	v_lshl_add_u64 v[110:111], v[10:11], 0, v[12:13]
	v_lshl_add_u64 v[10:11], s[20:21], 0, v[94:95]
	s_mov_b32 s24, 1
	v_lshl_add_u64 v[106:107], s[26:27], 0, v[88:89]
	v_lshl_add_u64 v[112:113], v[10:11], 0, v[12:13]
	s_mov_b32 s35, 0
	s_mov_b32 s50, 0
	s_mov_b32 s51, 0
	s_movk_i32 s29, 0x1000
	s_waitcnt vmcnt(0)
.LBB0_466:
	s_mov_b32 s100, 0
	v_add_u32_e32 v0, s50, v152
	v_lshl_add_u64 v[10:11], s[84:85], 0, v[108:109]
	s_mov_b32 s20, 0x37151000
	v_min_i32_e32 v0, 0x1ffe, v0
	v_add_co_u32_e32 v10, vcc, s20, v10
	v_add_u32_e32 v0, 1, v0
	s_nop 0
	v_addc_co_u32_e32 v11, vcc, 0, v11, vcc
	v_lshl_add_u64 v[12:13], s[80:81], 0, v[0:1]
	v_lshl_add_u64 v[34:35], s[84:85], 0, v[106:107]
	v_lshlrev_b64 v[12:13], 12, v[12:13]
	v_add_co_u32_e32 v18, vcc, 0x27060000, v34
	v_lshl_add_u64 v[12:13], v[100:101], 0, v[12:13]
	s_nop 0
	v_addc_co_u32_e32 v19, vcc, 0, v35, vcc
	global_load_dwordx4 v[26:29], v[10:11], off
	global_load_dwordx4 v[22:25], v[12:13], off
	s_nop 0
	global_load_dwordx4 v[18:21], v[18:19], off
	v_add_co_u32_e32 v12, vcc, 0x1f060000, v34
	s_nop 1
	v_addc_co_u32_e32 v13, vcc, 0, v35, vcc
	global_load_dwordx4 v[50:53], v[10:11], off offset:-4096
	global_load_dwordx4 v[34:37], v[12:13], off
	v_mov_b32_e32 v10, 0
	v_mov_b32_e32 v11, 0
	v_mov_b32_e32 v12, 0
	v_mov_b32_e32 v13, 0
	s_and_saveexec_b64 s[22:23], s[40:41]
	s_cbranch_execz .LBB0_468
	v_lshl_add_u64 v[10:11], s[84:85], 0, v[104:105]
	global_load_dwordx4 v[10:13], v[10:11], off
.LBB0_468:
	s_or_b64 exec, exec, s[22:23]
	v_cvt_f32_f16_sdwa v159, v54 dst_sel:DWORD dst_unused:UNUSED_PAD src0_sel:WORD_1
	v_cvt_f32_f16_e32 v158, v54
	v_cvt_f32_f16_e32 v54, v46
	v_cvt_f32_f16_sdwa v46, v46 dst_sel:DWORD dst_unused:UNUSED_PAD src0_sel:WORD_1
	s_and_b32 s20, 1, s51
	v_cvt_f32_f16_sdwa v161, v55 dst_sel:DWORD dst_unused:UNUSED_PAD src0_sel:WORD_1
	v_cvt_f32_f16_e32 v160, v55
	v_mul_f32_e32 v46, 0xbfb8aa3b, v46
	v_exp_f32_e32 v55, v46
	v_cvt_f32_f16_e32 v46, v47
	s_cselect_b32 s21, 0x12880, 0
	s_add_i32 s21, s21, 0
	v_add_u32_e32 v0, s21, v81
	v_add_u32_e32 v162, v0, v114
	v_mul_f32_e32 v46, 0xbfb8aa3b, v46
	ds_write_b128 v162, v[158:161]
	v_cvt_f32_f16_sdwa v159, v56 dst_sel:DWORD dst_unused:UNUSED_PAD src0_sel:WORD_1
	v_cvt_f32_f16_e32 v158, v56
	v_exp_f32_e32 v56, v46
	v_cvt_f32_f16_sdwa v46, v47 dst_sel:DWORD dst_unused:UNUSED_PAD src0_sel:WORD_1
	v_cvt_f32_f16_sdwa v161, v57 dst_sel:DWORD dst_unused:UNUSED_PAD src0_sel:WORD_1
	v_cvt_f32_f16_e32 v160, v57
	v_cvt_f32_f16_sdwa v47, v48 dst_sel:DWORD dst_unused:UNUSED_PAD src0_sel:WORD_1
	v_mul_f32_e32 v46, 0xbfb8aa3b, v46
	v_exp_f32_e32 v57, v46
	v_cvt_f32_f16_e32 v46, v48
	v_cvt_f32_f16_e32 v48, v49
	v_cvt_f32_f16_sdwa v49, v49 dst_sel:DWORD dst_unused:UNUSED_PAD src0_sel:WORD_1
	v_mul_f32_e32 v47, 0xbfb8aa3b, v47
	v_mul_f32_e32 v46, 0xbfb8aa3b, v46
	v_mul_f32_e32 v48, 0xbfb8aa3b, v48
	v_mul_f32_e32 v49, 0xbfb8aa3b, v49
	v_exp_f32_e32 v46, v46
	v_exp_f32_e32 v47, v47
	v_exp_f32_e32 v48, v48
	v_exp_f32_e32 v49, v49
	v_mul_f32_e32 v54, 0xbfb8aa3b, v54
	v_exp_f32_e32 v54, v54
	ds_write_b128 v162, v[158:161] offset:16
	ds_write_b128 v162, v[46:49] offset:8208
	v_cvt_f32_f16_sdwa v47, v42 dst_sel:DWORD dst_unused:UNUSED_PAD src0_sel:WORD_1
	v_cvt_f32_f16_e32 v46, v42
	v_cvt_f32_f16_sdwa v49, v43 dst_sel:DWORD dst_unused:UNUSED_PAD src0_sel:WORD_1
	v_cvt_f32_f16_e32 v48, v43
	v_cvt_f32_f16_sdwa v43, v38 dst_sel:DWORD dst_unused:UNUSED_PAD src0_sel:WORD_1
	v_cvt_f32_f16_e32 v42, v38
	v_cvt_f32_f16_e32 v38, v30
	ds_write_b128 v162, v[46:49] offset:16384
	v_cvt_f32_f16_sdwa v47, v44 dst_sel:DWORD dst_unused:UNUSED_PAD src0_sel:WORD_1
	v_cvt_f32_f16_e32 v46, v44
	v_cvt_f32_f16_sdwa v49, v45 dst_sel:DWORD dst_unused:UNUSED_PAD src0_sel:WORD_1
	v_cvt_f32_f16_e32 v48, v45
	v_cvt_f32_f16_sdwa v45, v39 dst_sel:DWORD dst_unused:UNUSED_PAD src0_sel:WORD_1
	v_cvt_f32_f16_e32 v44, v39
	v_cvt_f32_f16_sdwa v39, v30 dst_sel:DWORD dst_unused:UNUSED_PAD src0_sel:WORD_1
	ds_write_b128 v162, v[46:49] offset:16400
	v_cvt_f32_f16_sdwa v47, v40 dst_sel:DWORD dst_unused:UNUSED_PAD src0_sel:WORD_1
	v_cvt_f32_f16_e32 v46, v40
	v_cvt_f32_f16_sdwa v49, v41 dst_sel:DWORD dst_unused:UNUSED_PAD src0_sel:WORD_1
	v_cvt_f32_f16_e32 v48, v41
	v_cvt_f32_f16_sdwa v41, v31 dst_sel:DWORD dst_unused:UNUSED_PAD src0_sel:WORD_1
	v_cvt_f32_f16_e32 v40, v31
	ds_write_b128 v162, v[54:57] offset:8192
	v_cvt_f32_f16_sdwa v55, v32 dst_sel:DWORD dst_unused:UNUSED_PAD src0_sel:WORD_1
	v_cvt_f32_f16_e32 v54, v32
	v_pk_mul_f32 v[30:31], v[38:39], v[42:43]
	v_cvt_f32_f16_sdwa v57, v33 dst_sel:DWORD dst_unused:UNUSED_PAD src0_sel:WORD_1
	v_add_f32_e32 v30, 0, v30
	v_cvt_f32_f16_e32 v56, v33
	v_add_f32_e32 v32, v31, v30
	v_pk_mul_f32 v[30:31], v[40:41], v[44:45]
	ds_write_b128 v162, v[42:45] offset:24576
	v_add_f32_e32 v30, v30, v32
	v_add_f32_e32 v32, v31, v30
	v_pk_mul_f32 v[30:31], v[54:55], v[46:47]
	ds_write_b128 v162, v[46:49] offset:24592
	v_add_f32_e32 v30, v30, v32
	v_add_f32_e32 v32, v31, v30
	v_pk_mul_f32 v[30:31], v[56:57], v[48:49]
	ds_write_b128 v162, v[38:41] offset:32768
	v_add_f32_e32 v30, v30, v32
	v_add_f32_e32 v30, v31, v30
	ds_bpermute_b32 v31, v97, v30
	ds_write_b128 v162, v[54:57] offset:32784
	s_waitcnt lgkmcnt(1)
	v_add_f32_e32 v30, v30, v31
	ds_bpermute_b32 v31, v155, v30
	s_waitcnt lgkmcnt(0)
	v_add_f32_e32 v30, v30, v31
	ds_bpermute_b32 v31, v156, v30
	s_and_saveexec_b64 s[22:23], s[44:45]
	s_cbranch_execz .LBB0_470
	s_waitcnt lgkmcnt(0)
	v_add_f32_e32 v30, v30, v31
	v_add3_u32 v0, v0, v115, s6
	ds_write_b32 v0, v30

; #define LAS __attribute__((address_space(3)))
; __device__ __forceinline__ void scan_phase(LAS unsigned char* lds, const h16* C1, const h16* DEC, const h16* AA, const h16* BB, float* Y, ...
;     ...
;             auto yout = [&](int c, int bufi) {
; #pragma unroll
;                 for (int o2 = 0; o2 < 2; ++o2) {
;                     const int o = lt + 256 * o2, ys = o >> 4, yr = o & 15;
;                     LAS float* yp = L + bufi * BUF + 10752 + o * 16;
;                     f32x4 acc4 = *(LAS f32x4*)(yp + (((0 + (o >> 2)) & 3) << 2));
; #pragma unroll
;                     for (int i = 1; i < 4; ++i) acc4 += *(LAS f32x4*)(yp + (((i + (o >> 2)) & 3) << 2));
;                     Y[(row0 + (size_t)c * CH + ys) * DM + h * 64 + q * 16 + yr] = (acc4[0] + acc4[1]) + (acc4[2] + acc4[3]);
;                 }
;             };
;     ...
;             auto cvt_finish = [&]() {
;                 if (cdst == nullptr) return;
;                 const int ln = lt & 63, kr = ln >> 3, nc = (ln & 7) * 4;
; #pragma unroll
;                 for (int e = 0; e < 4; ++e) { ctile[(nc + e) * 16 + kr] = (h16)cv0[e]; ctile[(nc + e) * 16 + kr + 8] = (h16)cv1[e]; }
;                 asm volatile("s_waitcnt lgkmcnt(0)" ::: "memory");
;                 const h16x8 o = *(LAS h16x8*)(ctile + (ln & 31) * 16 + (ln >> 5) * 8);
;                 *(h16x8*)cdst = o;
;                 asm volatile("s_waitcnt lgkmcnt(0)" ::: "memory");
;             };
.LBB0_472:
	s_or_b64 exec, exec, s[22:23]
	s_cmp_eq_u32 s20, 1
	s_cselect_b32 s20, 0x12880, 0
	s_add_i32 s20, s20, 0
	v_add_u32_e32 v0, s20, v119
	v_add_u32_e32 v14, v0, v126
	v_add_u32_e32 v30, v0, v128
	ds_read_b128 v[14:17], v14 offset:43008
	s_waitcnt lgkmcnt(1)
	ds_read_b128 v[30:33], v30 offset:43008
	v_cmp_ne_u64_e32 vcc, 0, v[102:103]
	s_waitcnt lgkmcnt(0)
	v_pk_add_f32 v[30:31], v[14:15], v[30:31]
	v_add_u32_e32 v14, v0, v130
	v_pk_add_f32 v[32:33], v[16:17], v[32:33]
	ds_read_b128 v[14:17], v14 offset:43008
	v_add_u32_e32 v0, v0, v132
	s_waitcnt lgkmcnt(0)
	v_pk_add_f32 v[32:33], v[32:33], v[16:17]
	v_pk_add_f32 v[30:31], v[30:31], v[14:15]
	ds_read_b128 v[14:17], v0 offset:43008
	s_waitcnt lgkmcnt(0)
	v_pk_add_f32 v[16:17], v[32:33], v[16:17]
	v_pk_add_f32 v[14:15], v[30:31], v[14:15]
	s_nop 0
	v_add_f32_e32 v0, v14, v15
	v_add_f32_e32 v14, v16, v17
	v_add_f32_e32 v0, v0, v14
	v_lshl_add_u64 v[14:15], s[84:85], 0, v[112:113]
	global_store_dword v[14:15], v0, off
	v_add_u32_e32 v0, s20, v120
	v_add_u32_e32 v14, v0, v126
	v_add_u32_e32 v30, v0, v128
	ds_read_b128 v[14:17], v14 offset:43008
	ds_read_b128 v[30:33], v30 offset:43008
	s_waitcnt lgkmcnt(0)
	v_pk_add_f32 v[30:31], v[14:15], v[30:31]
	v_add_u32_e32 v14, v0, v130
	v_pk_add_f32 v[32:33], v[16:17], v[32:33]
	ds_read_b128 v[14:17], v14 offset:43008
	v_add_u32_e32 v0, v0, v132
	s_waitcnt lgkmcnt(0)
	v_pk_add_f32 v[32:33], v[32:33], v[16:17]
	v_pk_add_f32 v[30:31], v[30:31], v[14:15]
	ds_read_b128 v[14:17], v0 offset:43008
	s_waitcnt lgkmcnt(0)
	v_pk_add_f32 v[16:17], v[32:33], v[16:17]
	v_pk_add_f32 v[14:15], v[30:31], v[14:15]
	s_nop 0
	v_add_f32_e32 v0, v14, v15
	v_add_f32_e32 v14, v16, v17
	v_add_f32_e32 v0, v0, v14
	v_lshl_add_u64 v[14:15], s[84:85], 0, v[110:111]
	global_store_dword v[14:15], v0, off
	s_and_saveexec_b64 s[22:23], vcc
	s_cbranch_execz .LBB0_474
	s_bitset1_b32 s100, 0
	s_waitcnt vmcnt(7)
	v_cvt_f16_f32_e32 v0, v6
	v_add_u32_e32 v14, v123, v122
	ds_write_b16 v14, v0
	v_cvt_f16_f32_e32 v0, v2
	ds_write_b16 v14, v0 offset:16
	v_cvt_f16_f32_e32 v0, v7
	ds_write_b16 v14, v0 offset:32
	v_cvt_f16_f32_e32 v0, v3
	ds_write_b16 v14, v0 offset:48
	v_cvt_f16_f32_e32 v0, v8
	ds_write_b16 v14, v0 offset:64
	v_cvt_f16_f32_e32 v0, v4
	ds_write_b16 v14, v0 offset:80
	v_cvt_f16_f32_e32 v0, v9
	ds_write_b16 v14, v0 offset:96
	v_cvt_f16_f32_e32 v0, v5
	ds_write_b16 v14, v0 offset:112
	s_waitcnt lgkmcnt(0)
	ds_read_b128 v[14:17], v124
	s_waitcnt lgkmcnt(0)
	global_store_dwordx4 v[102:103], v[14:17], off
	s_waitcnt lgkmcnt(0)

; __device__ __forceinline__ void scan_phase(LAS unsigned char* lds, const h16* C1, const h16* DEC, const h16* AA, const h16* BB, float* Y, ...
;     ...
;             auto cvt_issue = [&](int tix) {
;                 constexpr int T0 = 128 * 192, T1 = 128 * 64, T2 = 128 * 344, T3 = 344 * 64;
;                 cdst = nullptr;
;                 constexpr int T4 = 3 * 128 * 64;
;                 if (tix >= T0 + T1 + 2 * (T2 + T3) + (sRKV2 ? T4 : 0)) return;
;                 const float* src; h16* dst; int Ks, Ns, rm = 0, t = tix;
;                 if (t >= T0 + T1 + 2 * (T2 + T3)) {
;                     t -= T0 + T1 + 2 * (T2 + T3);
;                     const int mi = t / (128 * 64); t -= mi * (128 * 64);
;                     src = sRKV2 + (size_t)mi * DM * DM; dst = (h16*)(Wc + W_B1) + (size_t)mi * DM * DM; Ks = DM; Ns = DM;
;                 }
;                 else if (t >= T0 + T1 + T2 + T3) {
;                     t -= T0 + T1 + T2 + T3;
;                     if (t < T2) { src = sUP0; dst = (h16*)(Wc + W_UP); Ks = DM; Ns = 2 * FF; rm = 1; }
;                     else { t -= T2; src = sDN0; dst = (h16*)(Wc + W_DN); Ks = FF; Ns = DM; }
;                 }
;                 else if (t < T0) { src = sQKV; dst = (h16*)(Wn + W_B1); Ks = DM; Ns = 6144; }
;                 else if (t < T0 + T1) { t -= T0; src = sWO; dst = (h16*)(Wn + W_WO); Ks = DM; Ns = DM; }
;                 else if (t < T0 + T1 + T2) { t -= T0 + T1; src = sUP; dst = (h16*)(Wn + W_UP); Ks = DM; Ns = 2 * FF; rm = 1; }
;                 else { t -= T0 + T1 + T2; src = sDN; dst = (h16*)(Wn + W_DN); Ks = FF; Ns = DM; }
;                 const int tk = Ks >> 4, k0 = (t % tk) * 16, n0 = (t / tk) * 32;
;                 const int ln = lt & 63, kr = ln >> 3, nc = (ln & 7) * 4;
;                 cv0 = *(const f32x4*)(src + (size_t)(k0 + kr) * Ns + n0 + nc); cv1 = *(const f32x4*)(src + (size_t)(k0 + kr + 8) * Ns + n0 + nc);
;                 const int n = ln & 31, hf = ln >> 5, no = n0 + n;
;                 const int nd = rm == 0 ? no : (no < FF ? (no >> 7) * 256 + (no & 127) : ((no - FF) >> 7) * 256 + 128 + ((no - FF) & 127));
;                 cdst = dst + (size_t)nd * Ks + k0 + hf * 8;
.LBB0_497:
	s_or_b64 exec, exec, s[42:43]
	v_lshrrev_b32_e32 v0, 4, v30
	v_cvt_f32_u32_e32 v7, v0
	v_sub_u32_e32 v16, 0, v0
	v_sub_u32_e32 v9, 0, v6
	v_max_i32_e32 v9, v6, v9
	v_rcp_iflag_f32_e32 v7, v7
	v_ashrrev_i32_e32 v8, 31, v6
	v_mul_f32_e32 v7, 0x4f7ffffe, v7
	v_cvt_u32_f32_e32 v7, v7
	v_mul_lo_u32 v16, v16, v7
	v_mul_hi_u32 v16, v7, v16
	v_add_u32_e32 v7, v7, v16
	v_mul_hi_u32 v7, v9, v7
	v_mul_lo_u32 v16, v7, v0
	v_sub_u32_e32 v9, v9, v16
	v_add_u32_e32 v17, 1, v7
	v_cmp_ge_u32_e32 vcc, v9, v0
	v_sub_u32_e32 v16, v9, v0
	s_nop 0
	v_cndmask_b32_e32 v7, v7, v17, vcc
	v_cndmask_b32_e32 v9, v9, v16, vcc
	v_add_u32_e32 v16, 1, v7
	v_cmp_ge_u32_e32 vcc, v9, v0
	s_nop 1
	v_cndmask_b32_e32 v7, v7, v16, vcc
	v_xor_b32_e32 v7, v7, v8
	v_sub_u32_e32 v31, v7, v8
	v_mul_lo_u32 v0, v31, v0
	v_sub_u32_e32 v0, v6, v0
	v_lshlrev_b32_e32 v16, 4, v0
	v_lshlrev_b32_e32 v32, 5, v31
	v_or_b32_e32 v38, v16, v121
	v_ashrrev_i32_e32 v33, 31, v32
	v_ashrrev_i32_e32 v17, 31, v16
	v_lshlrev_b64 v[8:9], 2, v[32:33]
	v_or_b32_e32 v33, 8, v38
	v_mul_lo_u32 v39, v4, v17
	v_mul_lo_u32 v0, v5, v38
	v_mad_u64_u32 v[6:7], s[20:21], v4, v38, 0
	v_mul_lo_u32 v38, v5, v33
	v_mad_u64_u32 v[4:5], s[20:21], v4, v33, 0
	v_add3_u32 v7, v7, v39, v0
	v_add3_u32 v5, v5, v39, v38
	v_lshl_add_u64 v[6:7], v[6:7], 2, v[2:3]
	v_lshl_add_u64 v[2:3], v[4:5], 2, v[2:3]
	v_lshl_add_u64 v[6:7], v[6:7], 0, v[8:9]
	v_lshlrev_b32_e32 v0, 2, v82
	v_lshl_add_u64 v[2:3], v[2:3], 0, v[8:9]
	v_lshl_add_u64 v[6:7], v[6:7], 0, v[0:1]
	v_lshl_add_u64 v[2:3], v[2:3], 0, v[0:1]
	s_bitset1_b32 s100, 1
	global_load_dwordx4 v[6:9], v[6:7], off
	s_nop 0
	global_load_dwordx4 v[2:5], v[2:3], off
	s_xor_b64 s[20:21], s[26:27], -1
	v_or_b32_e32 v0, v32, v125
	s_and_saveexec_b64 s[26:27], s[20:21]
	s_cbranch_execz .LBB0_503
	s_movk_i32 s4, 0x157f
	v_cmp_lt_i32_e32 vcc, s4, v0
	v_lshlrev_b32_e32 v31, 6, v31
	s_and_saveexec_b64 s[20:21], vcc
	s_xor_b64 s[42:43], exec, s[20:21]
	v_add_u32_e32 v31, 0x7fffd500, v31
	v_and_b32_e32 v31, 0x7fffff00, v31
	v_and_b32_e32 v0, 0x7f, v0
	v_or3_b32 v0, v31, v0, s66
	s_andn2_saveexec_b64 s[42:43], s[42:43]
	v_and_b32_e32 v31, 0xffffff00, v31
	s_movk_i32 s4, 0x7f
	v_and_or_b32 v0, v0, s4, v31
	s_or_b64 exec, exec, s[42:43]

; __device__ __forceinline__ void scan_phase(LAS unsigned char* lds, const h16* C1, const h16* DEC, const h16* AA, const h16* BB, float* Y, ...
;     ...
;             for (int c = 0; c < NCH; ++c) {
;                 StReg RB = RA;
;                 if (c + 2 < NCH) RB = gload(c + 2);
;                 if (c + 1 < NCH) lwrite(RA, (c + 1) & 1);
;                 if (c > 0) yout(c - 1, (c - 1) & 1);
;                 if (Wn) { cvt_finish(); cvt_issue(wgl + 1024 * c); }
;                 asm volatile("s_waitcnt lgkmcnt(0)" ::: "memory");
;                 __builtin_amdgcn_s_barrier();
;                 asm volatile("" ::: "memory");
;                 RA = RB;
;             }
.LBB0_504:
	s_or_b64 exec, exec, s[22:23]
	s_waitcnt lgkmcnt(0)
	s_barrier
	s_mov_b64 s[4:5], 0x70000
	s_add_i32 s51, s51, 1
	s_add_i32 s50, s50, 32
	v_lshl_add_u64 v[104:105], v[104:105], 0, s[4:5]
	v_lshl_add_u64 v[108:109], v[108:109], 0, s[4:5]
	s_addk_i32 s35, 0x400
	s_mov_b64 s[4:5], 0x40000
	s_add_i32 s24, s24, 1
	v_lshl_add_u64 v[106:107], v[106:107], 0, s[52:53]
	v_lshl_add_u64 v[110:111], v[110:111], 0, s[4:5]
	s_cmp_eq_u32 s35, 0x3f400
	v_lshl_add_u64 v[112:113], v[112:113], 0, s[4:5]
	s_cbranch_scc1 .LBB0_506
	s_cmp_eq_u32 s100, 3
	s_cbranch_scc1 .Lld_w5
	s_waitcnt vmcnt(2)
	s_branch .Lld_wdone
.Lld_w5:
	s_waitcnt vmcnt(5)
.Lld_wdone:
	v_mov_b64_e32 v[32:33], v[20:21]
	v_mov_b64_e32 v[40:41], v[24:25]
	v_mov_b64_e32 v[48:49], v[36:37]
	v_mov_b64_e32 v[56:57], v[52:53]
	v_mov_b64_e32 v[44:45], v[28:29]
	v_mov_b64_e32 v[30:31], v[18:19]
	v_mov_b64_e32 v[38:39], v[22:23]
	v_mov_b64_e32 v[46:47], v[34:35]
	v_mov_b64_e32 v[54:55], v[50:51]
	v_mov_b64_e32 v[42:43], v[26:27]
	v_mov_b32_e32 v14, v10
	v_mov_b32_e32 v15, v11
	v_mov_b32_e32 v16, v12
	v_mov_b32_e32 v17, v13
	s_branch .LBB0_466

; __global__ void __launch_bounds__(512, 2) fwd_megakernel(Params p) {
;     extern __shared__ __attribute__((aligned(16))) unsigned char shm[];
	.amdhsa_kernel _Z14fwd_megakernel6Params
		.amdhsa_group_segment_fixed_size 0
		.amdhsa_private_segment_fixed_size 0
		.amdhsa_kernarg_size 528
		.amdhsa_user_sgpr_count 2
		.amdhsa_user_sgpr_dispatch_ptr 0
		.amdhsa_user_sgpr_queue_ptr 0
		.amdhsa_user_sgpr_kernarg_segment_ptr 1
		.amdhsa_user_sgpr_dispatch_id 0
		.amdhsa_user_sgpr_kernarg_preload_length 0
		.amdhsa_user_sgpr_kernarg_preload_offset 0
		.amdhsa_user_sgpr_private_segment_size 0
		.amdhsa_uses_dynamic_stack 0
		.amdhsa_enable_private_segment 0
		.amdhsa_system_sgpr_workgroup_id_x 1
		.amdhsa_system_sgpr_workgroup_id_y 0
		.amdhsa_system_sgpr_workgroup_id_z 0
		.amdhsa_system_sgpr_workgroup_info 0
		.amdhsa_system_vgpr_workitem_id 2
		.amdhsa_next_free_vgpr 256
		.amdhsa_next_free_sgpr 102
		.amdhsa_accum_offset 256
		.amdhsa_reserve_vcc 1
		.amdhsa_float_round_mode_32 0
		.amdhsa_float_round_mode_16_64 0
		.amdhsa_float_denorm_mode_32 3
		.amdhsa_float_denorm_mode_16_64 3
		.amdhsa_dx10_clamp 1
		.amdhsa_ieee_mode 1
		.amdhsa_fp16_overflow 0
		.amdhsa_tg_split 0
		.amdhsa_exception_fp_ieee_invalid_op 0
		.amdhsa_exception_fp_denorm_src 0
		.amdhsa_exception_fp_ieee_div_zero 0
		.amdhsa_exception_fp_ieee_overflow 0
		.amdhsa_exception_fp_ieee_underflow 0
		.amdhsa_exception_fp_ieee_inexact 0
		.amdhsa_exception_int_div_zero 0
	.end_amdhsa_kernel

; __global__ void __launch_bounds__(512, 2) fwd_megakernel(Params p) {
;     extern __shared__ __attribute__((aligned(16))) unsigned char shm[];
amdhsa.kernels:
  - .agpr_count:     0
    .args:
      - .offset:         0
        .size:           272
        .value_kind:     by_value
      - .offset:         272
        .size:           4
        .value_kind:     hidden_block_count_x
      - .offset:         276
        .size:           4
        .value_kind:     hidden_block_count_y
      - .offset:         280
        .size:           4
        .value_kind:     hidden_block_count_z
      - .offset:         284
        .size:           2
        .value_kind:     hidden_group_size_x
      - .offset:         286
        .size:           2
        .value_kind:     hidden_group_size_y
      - .offset:         288
        .size:           2
        .value_kind:     hidden_group_size_z
      - .offset:         290
        .size:           2
        .value_kind:     hidden_remainder_x
      - .offset:         292
        .size:           2
        .value_kind:     hidden_remainder_y
      - .offset:         294
        .size:           2
        .value_kind:     hidden_remainder_z
      - .offset:         312
        .size:           8
        .value_kind:     hidden_global_offset_x
      - .offset:         320
        .size:           8
        .value_kind:     hidden_global_offset_y
      - .offset:         328
        .size:           8
        .value_kind:     hidden_global_offset_z
      - .offset:         336
        .size:           2
        .value_kind:     hidden_grid_dims
      - .offset:         360
        .size:           8
        .value_kind:     hidden_multigrid_sync_arg
      - .offset:         392
        .size:           4
        .value_kind:     hidden_dynamic_lds_size
    .group_segment_fixed_size: 0
    .kernarg_segment_align: 8
    .kernarg_segment_size: 528
    .language:       OpenCL C
    .language_version:
      - 2
      - 0
    .max_flat_workgroup_size: 512
    .name:           _Z14fwd_megakernel6Params
    .private_segment_fixed_size: 0
    .sgpr_count:     108
    .sgpr_spill_count: 309
    .symbol:         _Z14fwd_megakernel6Params.kd
    .uniform_work_group_size: 1
    .uses_dynamic_stack: false
    .vgpr_count:     256
    .vgpr_spill_count: 0
    .wavefront_size: 64
